# phase 12: tile epilogue keeps final residual in accumulator registers, final rmsnorm applied from registers (no h store + re-read)
# speedup vs baseline: 1.0202x; 1.0187x over previous
; __device__ __forceinline__ float bf_lo(unsigned w) { return __uint_as_float(w << 16); }
; __device__ __forceinline__ float bf_hi(unsigned w) { return __uint_as_float(w & 0xffff0000u); }
; __device__ __forceinline__ float sigmoidf_(float x) { return __builtin_amdgcn_rcpf(1.0f + __expf(-x)); }
;     __device__ __forceinline__ void operator()(const AccT& acc, const pg8::Unit& u, int wr, int wc, int fr, int fq) const {
;         asm volatile("" : "+v"(fr), "+v"(fq), "+s"(wr), "+s"(wc));
; #pragma unroll
;         for (int ai = 0; ai < 2; ++ai)
; #pragma unroll
;             for (int mp = 0; mp < 2; ++mp) {
;                 f32x4 hv[2][2][2]; u32x4 pw[2][2]; float rs[2];
; #pragma unroll
;                 for (int mm = 0; mm < 2; ++mm) { const int r = EPI_ROW(u, ai, 2 * mp + mm); rs[mm] = ssq_in[r];
; #pragma unroll
;                     for (int bj = 0; bj < 2; ++bj) { const int c = EPI_COL(u, bj); const float* hp = h + (size_t)r * D + c; hv[mm][bj][0] = *(const f32x4*)hp; hv[mm][bj][1] = *(const f32x4*)(hp + 4); pw[mm][bj] = *(const u32x4*)(pp + (size_t)r * D + c); } }
; #pragma unroll
;                 for (int mm = 0; mm < 2; ++mm) { const int m = 2 * mp + mm, r = EPI_ROW(u, ai, m); float s = 0.f; const float ri = rinv_of(rs[mm]);
; #pragma unroll
;                     for (int bj = 0; bj < 2; ++bj) { const int c = EPI_COL(u, bj); float* hp = h + (size_t)r * D + c; const u32x4 p4 = pw[mm][bj];
;                         const f32x4 a0 = acc[ai][bj][m][0] * ri, a1 = acc[ai][bj][m][1] * ri; f32x4 v0 = hv[mm][bj][0], v1 = hv[mm][bj][1];
;                         v0[0] += mul * sigmoidf_(a0[0]) * bf_lo(p4.x); v0[1] += mul * sigmoidf_(a0[1]) * bf_hi(p4.x); v0[2] += mul * sigmoidf_(a0[2]) * bf_lo(p4.y); v0[3] += mul * sigmoidf_(a0[3]) * bf_hi(p4.y);
;                         v1[0] += mul * sigmoidf_(a1[0]) * bf_lo(p4.z); v1[1] += mul * sigmoidf_(a1[1]) * bf_hi(p4.z); v1[2] += mul * sigmoidf_(a1[2]) * bf_lo(p4.w); v1[3] += mul * sigmoidf_(a1[3]) * bf_hi(p4.w);
;                         *(f32x4*)hp = v0; *(f32x4*)(hp + 4) = v1;
;                         if (hb) *(u32x4*)(hb + (size_t)r * D + c) = pack8(v0, v1);
;                         s += sq8(v0, v1); }
;                     ssq_commit(s, ssq, r, fq); }
;                 asm volatile("" ::: "memory"); }
;     }
.LBB0_2621:
	s_lshl_b32 s12, s36, 8
	s_lshl_b32 s13, s42, 6
	s_add_i32 s12, s12, s13
	v_add_u32_e32 v241, s12, v180
	s_lshl_b32 s12, s34, 8
	s_lshl_b32 s13, s47, 5
	s_add_i32 s12, s12, s13
	v_lshl_add_u32 v242, v181, 3, s12
	v_lshlrev_b32_e32 v243, 12, v241
	v_lshl_add_u32 v243, v242, 2, v243
	v_lshlrev_b32_e32 v226, 2, v241
	v_mov_b32_e32 v225, 0x358637bd
	v_mbcnt_lo_u32_b32 v224, -1, 0
	v_mbcnt_hi_u32_b32 v224, -1, v224
	v_lshlrev_b32_e32 v224, 2, v224
	v_cmp_eq_u32_e64 s[98:99], 0, v181
	v_mov_b32_e32 v232, v243
	v_lshrrev_b32_e32 v233, 1, v232
	global_load_dword v176, v226, s[14:15]
	global_load_dwordx4 v[128:131], v232, s[52:53]
	global_load_dwordx4 v[132:135], v232, s[52:53] offset:16
	global_load_dwordx4 v[136:139], v232, s[52:53] offset:512
	global_load_dwordx4 v[140:143], v232, s[52:53] offset:528
	global_load_dwordx4 v[144:147], v233, s[72:73]
	global_load_dwordx4 v[148:151], v233, s[72:73] offset:256
	v_add_u32_e32 v232, 0x10000, v243
	v_lshrrev_b32_e32 v233, 1, v232
	global_load_dword v177, v226, s[14:15] offset:64
	global_load_dwordx4 v[152:155], v232, s[52:53]
	global_load_dwordx4 v[156:159], v232, s[52:53] offset:16
	global_load_dwordx4 v[160:163], v232, s[52:53] offset:512
	global_load_dwordx4 v[164:167], v232, s[52:53] offset:528
	global_load_dwordx4 v[168:171], v233, s[72:73]
	global_load_dwordx4 v[172:175], v233, s[72:73] offset:256
	v_add_u32_e32 v232, 0x20000, v243
	v_lshrrev_b32_e32 v233, 1, v232
	global_load_dword v227, v226, s[14:15] offset:128
	global_load_dwordx4 v[178:181], v232, s[52:53]
	global_load_dwordx4 v[182:185], v232, s[52:53] offset:16
	global_load_dwordx4 v[186:189], v232, s[52:53] offset:512
	global_load_dwordx4 v[190:193], v232, s[52:53] offset:528
	global_load_dwordx4 v[212:215], v233, s[72:73]
	global_load_dwordx4 v[216:219], v233, s[72:73] offset:256
	v_add_u32_e32 v232, 0x30000, v243
	v_lshrrev_b32_e32 v233, 1, v232
	global_load_dword v228, v226, s[14:15] offset:192
	global_load_dwordx4 v[194:197], v232, s[52:53]
	global_load_dwordx4 v[198:201], v232, s[52:53] offset:16
	global_load_dwordx4 v[202:205], v232, s[52:53] offset:512
	global_load_dwordx4 v[206:209], v232, s[52:53] offset:528
	global_load_dwordx4 v[220:223], v233, s[72:73]
	global_load_dwordx4 v[244:247], v233, s[72:73] offset:256
	s_waitcnt vmcnt(21)
	v_fmamk_f32 v230, v176, 0x3a800000, v225
	v_rsq_f32_e32 v230, v230
	v_mov_b32_e32 v229, 0
	v_pk_mul_f32 v[236:237], v[124:125], v[230:231] op_sel_hi:[1,0]
	v_pk_mul_f32 v[238:239], v[126:127], v[230:231] op_sel_hi:[1,0]
	v_mul_f32_e32 v236, 0xbfb8aa3b, v236
	v_mul_f32_e32 v237, 0xbfb8aa3b, v237
	v_mul_f32_e32 v238, 0xbfb8aa3b, v238
	v_mul_f32_e32 v239, 0xbfb8aa3b, v239
	v_exp_f32_e32 v236, v236
	v_exp_f32_e32 v237, v237
	v_exp_f32_e32 v238, v238
	v_exp_f32_e32 v239, v239
	v_add_f32_e32 v236, 1.0, v236
	v_add_f32_e32 v237, 1.0, v237
	v_add_f32_e32 v238, 1.0, v238
	v_add_f32_e32 v239, 1.0, v239
	v_rcp_f32_e32 v236, v236
	v_rcp_f32_e32 v237, v237
	v_rcp_f32_e32 v238, v238
	v_rcp_f32_e32 v239, v239
	v_lshlrev_b32_e32 v232, 16, v144
	v_and_b32_e32 v233, 0xffff0000, v144
	v_lshlrev_b32_e32 v234, 16, v145
	v_and_b32_e32 v235, 0xffff0000, v145
	v_pk_fma_f32 v[124:125], v[236:237], v[232:233], v[128:129]
	v_pk_fma_f32 v[126:127], v[238:239], v[234:235], v[130:131]
	v_pk_mul_f32 v[236:237], v[124:125], v[124:125]
	v_pk_mul_f32 v[238:239], v[126:127], v[126:127]
	v_add_f32_e32 v229, v229, v236
	v_add_f32_e32 v229, v229, v237
	v_add_f32_e32 v229, v229, v238
	v_add_f32_e32 v229, v229, v239
	v_pk_mul_f32 v[236:237], v[120:121], v[230:231] op_sel_hi:[1,0]
	v_pk_mul_f32 v[238:239], v[122:123], v[230:231] op_sel_hi:[1,0]
	v_mul_f32_e32 v236, 0xbfb8aa3b, v236
	v_mul_f32_e32 v237, 0xbfb8aa3b, v237
	v_mul_f32_e32 v238, 0xbfb8aa3b, v238
	v_mul_f32_e32 v239, 0xbfb8aa3b, v239
	v_exp_f32_e32 v236, v236
	v_exp_f32_e32 v237, v237
	v_exp_f32_e32 v238, v238
	v_exp_f32_e32 v239, v239
	v_add_f32_e32 v236, 1.0, v236
	v_add_f32_e32 v237, 1.0, v237
	v_add_f32_e32 v238, 1.0, v238
	v_add_f32_e32 v239, 1.0, v239
	v_rcp_f32_e32 v236, v236
	v_rcp_f32_e32 v237, v237
	v_rcp_f32_e32 v238, v238
	v_rcp_f32_e32 v239, v239
	v_lshlrev_b32_e32 v232, 16, v146
	v_and_b32_e32 v233, 0xffff0000, v146
	v_lshlrev_b32_e32 v234, 16, v147
	v_and_b32_e32 v235, 0xffff0000, v147
	v_pk_fma_f32 v[120:121], v[236:237], v[232:233], v[132:133]
	v_pk_fma_f32 v[122:123], v[238:239], v[234:235], v[134:135]
	v_pk_mul_f32 v[236:237], v[120:121], v[120:121]
	v_pk_mul_f32 v[238:239], v[122:123], v[122:123]
	v_add_f32_e32 v229, v229, v236
	v_add_f32_e32 v229, v229, v237
	v_add_f32_e32 v229, v229, v238
	v_add_f32_e32 v229, v229, v239
	v_pk_mul_f32 v[236:237], v[116:117], v[230:231] op_sel_hi:[1,0]
	v_pk_mul_f32 v[238:239], v[118:119], v[230:231] op_sel_hi:[1,0]
	v_mul_f32_e32 v236, 0xbfb8aa3b, v236
	v_mul_f32_e32 v237, 0xbfb8aa3b, v237
	v_mul_f32_e32 v238, 0xbfb8aa3b, v238
	v_mul_f32_e32 v239, 0xbfb8aa3b, v239
	v_exp_f32_e32 v236, v236
	v_exp_f32_e32 v237, v237
	v_exp_f32_e32 v238, v238
	v_exp_f32_e32 v239, v239
	v_add_f32_e32 v236, 1.0, v236
	v_add_f32_e32 v237, 1.0, v237
	v_add_f32_e32 v238, 1.0, v238
	v_add_f32_e32 v239, 1.0, v239
	v_rcp_f32_e32 v236, v236
	v_rcp_f32_e32 v237, v237
	v_rcp_f32_e32 v238, v238
	v_rcp_f32_e32 v239, v239
	v_lshlrev_b32_e32 v232, 16, v148
	v_and_b32_e32 v233, 0xffff0000, v148
	v_lshlrev_b32_e32 v234, 16, v149
	v_and_b32_e32 v235, 0xffff0000, v149
	v_pk_fma_f32 v[116:117], v[236:237], v[232:233], v[136:137]
	v_pk_fma_f32 v[118:119], v[238:239], v[234:235], v[138:139]
	v_pk_mul_f32 v[236:237], v[116:117], v[116:117]
	v_pk_mul_f32 v[238:239], v[118:119], v[118:119]
	v_add_f32_e32 v229, v229, v236
	v_add_f32_e32 v229, v229, v237
	v_add_f32_e32 v229, v229, v238
	v_add_f32_e32 v229, v229, v239
	v_pk_mul_f32 v[236:237], v[112:113], v[230:231] op_sel_hi:[1,0]
	v_pk_mul_f32 v[238:239], v[114:115], v[230:231] op_sel_hi:[1,0]
	v_mul_f32_e32 v236, 0xbfb8aa3b, v236
	v_mul_f32_e32 v237, 0xbfb8aa3b, v237
	v_mul_f32_e32 v238, 0xbfb8aa3b, v238
	v_mul_f32_e32 v239, 0xbfb8aa3b, v239
	v_exp_f32_e32 v236, v236
	v_exp_f32_e32 v237, v237
	v_exp_f32_e32 v238, v238
	v_exp_f32_e32 v239, v239
	v_add_f32_e32 v236, 1.0, v236
	v_add_f32_e32 v237, 1.0, v237
	v_add_f32_e32 v238, 1.0, v238
	v_add_f32_e32 v239, 1.0, v239
	v_rcp_f32_e32 v236, v236
	v_rcp_f32_e32 v237, v237
	v_rcp_f32_e32 v238, v238
	v_rcp_f32_e32 v239, v239
	v_lshlrev_b32_e32 v232, 16, v150
	v_and_b32_e32 v233, 0xffff0000, v150
	v_lshlrev_b32_e32 v234, 16, v151
	v_and_b32_e32 v235, 0xffff0000, v151
	v_pk_fma_f32 v[112:113], v[236:237], v[232:233], v[140:141]
	v_pk_fma_f32 v[114:115], v[238:239], v[234:235], v[142:143]
	v_pk_mul_f32 v[236:237], v[112:113], v[112:113]
	v_pk_mul_f32 v[238:239], v[114:115], v[114:115]
	v_add_f32_e32 v229, v229, v236
	v_add_f32_e32 v229, v229, v237
	v_add_f32_e32 v229, v229, v238
	v_add_f32_e32 v229, v229, v239
	v_xor_b32_e32 v232, 64, v224
	ds_bpermute_b32 v233, v232, v229
	s_waitcnt lgkmcnt(0)
; __device__ __forceinline__ float bf_lo(unsigned w) { return __uint_as_float(w << 16); }
; __device__ __forceinline__ float bf_hi(unsigned w) { return __uint_as_float(w & 0xffff0000u); }
; __device__ __forceinline__ float sigmoidf_(float x) { return __builtin_amdgcn_rcpf(1.0f + __expf(-x)); }
; __device__ __forceinline__ float rinv_of(float ssq) { return rsqrtf(ssq * (1.0f / 1024.0f) + EPS); }
; __device__ __forceinline__ u32x4 pack8(const f32x4 a, const f32x4 b) { u32x4 w; w.x = cvt_pk_bf16(a[0], a[1]); w.y = cvt_pk_bf16(a[2], a[3]); w.z = cvt_pk_bf16(b[0], b[1]); w.w = cvt_pk_bf16(b[2], b[3]); return w; }
;     __device__ __forceinline__ void operator()(const AccT& acc, const pg8::Unit& u, int wr, int wc, int fr, int fq) const {
;     ...
;                 for (int mm = 0; mm < 2; ++mm) { const int r = EPI_ROW(u, ai, 2 * mp + mm); rs[mm] = ssq_in[r];
; #pragma unroll
;                     for (int bj = 0; bj < 2; ++bj) { const int c = EPI_COL(u, bj); const float* hp = h + (size_t)r * D + c; hv[mm][bj][0] = *(const f32x4*)hp; hv[mm][bj][1] = *(const f32x4*)(hp + 4); pw[mm][bj] = *(const u32x4*)(pp + (size_t)r * D + c); } }
; #pragma unroll
;                 for (int mm = 0; mm < 2; ++mm) { const int m = 2 * mp + mm, r = EPI_ROW(u, ai, m); float s = 0.f; const float ri = rinv_of(rs[mm]);
; #pragma unroll
;                     for (int bj = 0; bj < 2; ++bj) { const int c = EPI_COL(u, bj); float* hp = h + (size_t)r * D + c; const u32x4 p4 = pw[mm][bj];
;                         const f32x4 a0 = acc[ai][bj][m][0] * ri, a1 = acc[ai][bj][m][1] * ri; f32x4 v0 = hv[mm][bj][0], v1 = hv[mm][bj][1];
;                         v0[0] += mul * sigmoidf_(a0[0]) * bf_lo(p4.x); v0[1] += mul * sigmoidf_(a0[1]) * bf_hi(p4.x); v0[2] += mul * sigmoidf_(a0[2]) * bf_lo(p4.y); v0[3] += mul * sigmoidf_(a0[3]) * bf_hi(p4.y);
;                         v1[0] += mul * sigmoidf_(a1[0]) * bf_lo(p4.z); v1[1] += mul * sigmoidf_(a1[1]) * bf_hi(p4.z); v1[2] += mul * sigmoidf_(a1[2]) * bf_lo(p4.w); v1[3] += mul * sigmoidf_(a1[3]) * bf_hi(p4.w);
;                         *(f32x4*)hp = v0; *(f32x4*)(hp + 4) = v1;
;                         if (hb) *(u32x4*)(hb + (size_t)r * D + c) = pack8(v0, v1);
;                         s += sq8(v0, v1); }
;                     ssq_commit(s, ssq, r, fq); }
	v_add_f32_e32 v229, v229, v233
	v_xor_b32_e32 v232, 0x80, v224
	ds_bpermute_b32 v233, v232, v229
	s_waitcnt lgkmcnt(0)
	v_add_f32_e32 v229, v229, v233
	s_and_saveexec_b64 s[100:101], s[98:99]
	global_atomic_add_f32 v226, v229, s[16:17]
	s_mov_b64 exec, s[100:101]
	s_waitcnt vmcnt(15)
	v_fmamk_f32 v230, v177, 0x3a800000, v225
	v_rsq_f32_e32 v230, v230
	v_mov_b32_e32 v229, 0
	v_pk_mul_f32 v[236:237], v[108:109], v[230:231] op_sel_hi:[1,0]
	v_pk_mul_f32 v[238:239], v[110:111], v[230:231] op_sel_hi:[1,0]
	v_mul_f32_e32 v236, 0xbfb8aa3b, v236
	v_mul_f32_e32 v237, 0xbfb8aa3b, v237
	v_mul_f32_e32 v238, 0xbfb8aa3b, v238
	v_mul_f32_e32 v239, 0xbfb8aa3b, v239
	v_exp_f32_e32 v236, v236
	v_exp_f32_e32 v237, v237
	v_exp_f32_e32 v238, v238
	v_exp_f32_e32 v239, v239
	v_add_f32_e32 v236, 1.0, v236
	v_add_f32_e32 v237, 1.0, v237
	v_add_f32_e32 v238, 1.0, v238
	v_add_f32_e32 v239, 1.0, v239
	v_rcp_f32_e32 v236, v236
	v_rcp_f32_e32 v237, v237
	v_rcp_f32_e32 v238, v238
	v_rcp_f32_e32 v239, v239
	v_lshlrev_b32_e32 v232, 16, v168
	v_and_b32_e32 v233, 0xffff0000, v168
	v_lshlrev_b32_e32 v234, 16, v169
	v_and_b32_e32 v235, 0xffff0000, v169
	v_pk_fma_f32 v[108:109], v[236:237], v[232:233], v[152:153]
	v_pk_fma_f32 v[110:111], v[238:239], v[234:235], v[154:155]
	v_pk_mul_f32 v[236:237], v[108:109], v[108:109]
	v_pk_mul_f32 v[238:239], v[110:111], v[110:111]
	v_add_f32_e32 v229, v229, v236
	v_add_f32_e32 v229, v229, v237
	v_add_f32_e32 v229, v229, v238
	v_add_f32_e32 v229, v229, v239
	v_pk_mul_f32 v[236:237], v[104:105], v[230:231] op_sel_hi:[1,0]
	v_pk_mul_f32 v[238:239], v[106:107], v[230:231] op_sel_hi:[1,0]
	v_mul_f32_e32 v236, 0xbfb8aa3b, v236
	v_mul_f32_e32 v237, 0xbfb8aa3b, v237
	v_mul_f32_e32 v238, 0xbfb8aa3b, v238
	v_mul_f32_e32 v239, 0xbfb8aa3b, v239
	v_exp_f32_e32 v236, v236
	v_exp_f32_e32 v237, v237
	v_exp_f32_e32 v238, v238
	v_exp_f32_e32 v239, v239
	v_add_f32_e32 v236, 1.0, v236
	v_add_f32_e32 v237, 1.0, v237
	v_add_f32_e32 v238, 1.0, v238
	v_add_f32_e32 v239, 1.0, v239
	v_rcp_f32_e32 v236, v236
	v_rcp_f32_e32 v237, v237
	v_rcp_f32_e32 v238, v238
	v_rcp_f32_e32 v239, v239
	v_lshlrev_b32_e32 v232, 16, v170
	v_and_b32_e32 v233, 0xffff0000, v170
	v_lshlrev_b32_e32 v234, 16, v171
	v_and_b32_e32 v235, 0xffff0000, v171
	v_pk_fma_f32 v[104:105], v[236:237], v[232:233], v[156:157]
	v_pk_fma_f32 v[106:107], v[238:239], v[234:235], v[158:159]
	v_pk_mul_f32 v[236:237], v[104:105], v[104:105]
	v_pk_mul_f32 v[238:239], v[106:107], v[106:107]
	v_add_f32_e32 v229, v229, v236
	v_add_f32_e32 v229, v229, v237
	v_add_f32_e32 v229, v229, v238
	v_add_f32_e32 v229, v229, v239
	v_pk_mul_f32 v[236:237], v[100:101], v[230:231] op_sel_hi:[1,0]
	v_pk_mul_f32 v[238:239], v[102:103], v[230:231] op_sel_hi:[1,0]
	v_mul_f32_e32 v236, 0xbfb8aa3b, v236
	v_mul_f32_e32 v237, 0xbfb8aa3b, v237
	v_mul_f32_e32 v238, 0xbfb8aa3b, v238
	v_mul_f32_e32 v239, 0xbfb8aa3b, v239
	v_exp_f32_e32 v236, v236
	v_exp_f32_e32 v237, v237
	v_exp_f32_e32 v238, v238
	v_exp_f32_e32 v239, v239
	v_add_f32_e32 v236, 1.0, v236
	v_add_f32_e32 v237, 1.0, v237
	v_add_f32_e32 v238, 1.0, v238
	v_add_f32_e32 v239, 1.0, v239
	v_rcp_f32_e32 v236, v236
	v_rcp_f32_e32 v237, v237
	v_rcp_f32_e32 v238, v238
	v_rcp_f32_e32 v239, v239
	v_lshlrev_b32_e32 v232, 16, v172
	v_and_b32_e32 v233, 0xffff0000, v172
	v_lshlrev_b32_e32 v234, 16, v173
	v_and_b32_e32 v235, 0xffff0000, v173
	v_pk_fma_f32 v[100:101], v[236:237], v[232:233], v[160:161]
	v_pk_fma_f32 v[102:103], v[238:239], v[234:235], v[162:163]
	v_pk_mul_f32 v[236:237], v[100:101], v[100:101]
	v_pk_mul_f32 v[238:239], v[102:103], v[102:103]
	v_add_f32_e32 v229, v229, v236
	v_add_f32_e32 v229, v229, v237
	v_add_f32_e32 v229, v229, v238
	v_add_f32_e32 v229, v229, v239
	v_pk_mul_f32 v[236:237], v[96:97], v[230:231] op_sel_hi:[1,0]
	v_pk_mul_f32 v[238:239], v[98:99], v[230:231] op_sel_hi:[1,0]
	v_mul_f32_e32 v236, 0xbfb8aa3b, v236
	v_mul_f32_e32 v237, 0xbfb8aa3b, v237
	v_mul_f32_e32 v238, 0xbfb8aa3b, v238
	v_mul_f32_e32 v239, 0xbfb8aa3b, v239
	v_exp_f32_e32 v236, v236
	v_exp_f32_e32 v237, v237
	v_exp_f32_e32 v238, v238
	v_exp_f32_e32 v239, v239
	v_add_f32_e32 v236, 1.0, v236
	v_add_f32_e32 v237, 1.0, v237
	v_add_f32_e32 v238, 1.0, v238
	v_add_f32_e32 v239, 1.0, v239
	v_rcp_f32_e32 v236, v236
	v_rcp_f32_e32 v237, v237
	v_rcp_f32_e32 v238, v238
	v_rcp_f32_e32 v239, v239
	v_lshlrev_b32_e32 v232, 16, v174
	v_and_b32_e32 v233, 0xffff0000, v174
	v_lshlrev_b32_e32 v234, 16, v175
	v_and_b32_e32 v235, 0xffff0000, v175
	v_pk_fma_f32 v[96:97], v[236:237], v[232:233], v[164:165]
	v_pk_fma_f32 v[98:99], v[238:239], v[234:235], v[166:167]
	v_pk_mul_f32 v[236:237], v[96:97], v[96:97]
	v_pk_mul_f32 v[238:239], v[98:99], v[98:99]
	v_add_f32_e32 v229, v229, v236
	v_add_f32_e32 v229, v229, v237
	v_add_f32_e32 v229, v229, v238
	v_add_f32_e32 v229, v229, v239
	v_xor_b32_e32 v232, 64, v224
	ds_bpermute_b32 v233, v232, v229
	s_waitcnt lgkmcnt(0)
	v_add_f32_e32 v229, v229, v233
	v_xor_b32_e32 v232, 0x80, v224
	ds_bpermute_b32 v233, v232, v229
	s_waitcnt lgkmcnt(0)
	v_add_f32_e32 v229, v229, v233
	s_and_saveexec_b64 s[100:101], s[98:99]
	global_atomic_add_f32 v226, v229, s[16:17] offset:64
	s_mov_b64 exec, s[100:101]
	v_add_u32_e32 v232, 0x80000, v243
	v_lshrrev_b32_e32 v233, 1, v232
	global_load_dword v176, v226, s[14:15] offset:512
	global_load_dwordx4 v[128:131], v232, s[52:53]
	global_load_dwordx4 v[132:135], v232, s[52:53] offset:16
	global_load_dwordx4 v[136:139], v232, s[52:53] offset:512
	global_load_dwordx4 v[140:143], v232, s[52:53] offset:528
	global_load_dwordx4 v[144:147], v233, s[72:73]
	global_load_dwordx4 v[148:151], v233, s[72:73] offset:256
	v_add_u32_e32 v232, 0x90000, v243
	v_lshrrev_b32_e32 v233, 1, v232
	global_load_dword v177, v226, s[14:15] offset:576
	global_load_dwordx4 v[152:155], v232, s[52:53]
	global_load_dwordx4 v[156:159], v232, s[52:53] offset:16
	global_load_dwordx4 v[160:163], v232, s[52:53] offset:512
	global_load_dwordx4 v[164:167], v232, s[52:53] offset:528
	global_load_dwordx4 v[168:171], v233, s[72:73]
	global_load_dwordx4 v[172:175], v233, s[72:73] offset:256
	s_waitcnt vmcnt(23)
; __device__ __forceinline__ float bf_lo(unsigned w) { return __uint_as_float(w << 16); }
; __device__ __forceinline__ float bf_hi(unsigned w) { return __uint_as_float(w & 0xffff0000u); }
; __device__ __forceinline__ float sigmoidf_(float x) { return __builtin_amdgcn_rcpf(1.0f + __expf(-x)); }
; __device__ __forceinline__ float rinv_of(float ssq) { return rsqrtf(ssq * (1.0f / 1024.0f) + EPS); }
; __device__ __forceinline__ u32x4 pack8(const f32x4 a, const f32x4 b) { u32x4 w; w.x = cvt_pk_bf16(a[0], a[1]); w.y = cvt_pk_bf16(a[2], a[3]); w.z = cvt_pk_bf16(b[0], b[1]); w.w = cvt_pk_bf16(b[2], b[3]); return w; }
;     __device__ __forceinline__ void operator()(const AccT& acc, const pg8::Unit& u, int wr, int wc, int fr, int fq) const {
;     ...
;                 for (int mm = 0; mm < 2; ++mm) { const int r = EPI_ROW(u, ai, 2 * mp + mm); rs[mm] = ssq_in[r];
; #pragma unroll
;                     for (int bj = 0; bj < 2; ++bj) { const int c = EPI_COL(u, bj); const float* hp = h + (size_t)r * D + c; hv[mm][bj][0] = *(const f32x4*)hp; hv[mm][bj][1] = *(const f32x4*)(hp + 4); pw[mm][bj] = *(const u32x4*)(pp + (size_t)r * D + c); } }
; #pragma unroll
;                 for (int mm = 0; mm < 2; ++mm) { const int m = 2 * mp + mm, r = EPI_ROW(u, ai, m); float s = 0.f; const float ri = rinv_of(rs[mm]);
; #pragma unroll
;                     for (int bj = 0; bj < 2; ++bj) { const int c = EPI_COL(u, bj); float* hp = h + (size_t)r * D + c; const u32x4 p4 = pw[mm][bj];
;                         const f32x4 a0 = acc[ai][bj][m][0] * ri, a1 = acc[ai][bj][m][1] * ri; f32x4 v0 = hv[mm][bj][0], v1 = hv[mm][bj][1];
;                         v0[0] += mul * sigmoidf_(a0[0]) * bf_lo(p4.x); v0[1] += mul * sigmoidf_(a0[1]) * bf_hi(p4.x); v0[2] += mul * sigmoidf_(a0[2]) * bf_lo(p4.y); v0[3] += mul * sigmoidf_(a0[3]) * bf_hi(p4.y);
;                         v1[0] += mul * sigmoidf_(a1[0]) * bf_lo(p4.z); v1[1] += mul * sigmoidf_(a1[1]) * bf_hi(p4.z); v1[2] += mul * sigmoidf_(a1[2]) * bf_lo(p4.w); v1[3] += mul * sigmoidf_(a1[3]) * bf_hi(p4.w);
;                         *(f32x4*)hp = v0; *(f32x4*)(hp + 4) = v1;
;                         if (hb) *(u32x4*)(hb + (size_t)r * D + c) = pack8(v0, v1);
;                         s += sq8(v0, v1); }
;                     ssq_commit(s, ssq, r, fq); }
	v_fmamk_f32 v230, v227, 0x3a800000, v225
	v_rsq_f32_e32 v230, v230
	v_mov_b32_e32 v229, 0
	v_pk_mul_f32 v[236:237], v[92:93], v[230:231] op_sel_hi:[1,0]
	v_pk_mul_f32 v[238:239], v[94:95], v[230:231] op_sel_hi:[1,0]
	v_mul_f32_e32 v236, 0xbfb8aa3b, v236
	v_mul_f32_e32 v237, 0xbfb8aa3b, v237
	v_mul_f32_e32 v238, 0xbfb8aa3b, v238
	v_mul_f32_e32 v239, 0xbfb8aa3b, v239
	v_exp_f32_e32 v236, v236
	v_exp_f32_e32 v237, v237
	v_exp_f32_e32 v238, v238
	v_exp_f32_e32 v239, v239
	v_add_f32_e32 v236, 1.0, v236
	v_add_f32_e32 v237, 1.0, v237
	v_add_f32_e32 v238, 1.0, v238
	v_add_f32_e32 v239, 1.0, v239
	v_rcp_f32_e32 v236, v236
	v_rcp_f32_e32 v237, v237
	v_rcp_f32_e32 v238, v238
	v_rcp_f32_e32 v239, v239
	v_lshlrev_b32_e32 v232, 16, v212
	v_and_b32_e32 v233, 0xffff0000, v212
	v_lshlrev_b32_e32 v234, 16, v213
	v_and_b32_e32 v235, 0xffff0000, v213
	v_pk_fma_f32 v[92:93], v[236:237], v[232:233], v[178:179]
	v_pk_fma_f32 v[94:95], v[238:239], v[234:235], v[180:181]
	v_pk_mul_f32 v[236:237], v[92:93], v[92:93]
	v_pk_mul_f32 v[238:239], v[94:95], v[94:95]
	v_add_f32_e32 v229, v229, v236
	v_add_f32_e32 v229, v229, v237
	v_add_f32_e32 v229, v229, v238
	v_add_f32_e32 v229, v229, v239
	v_pk_mul_f32 v[236:237], v[88:89], v[230:231] op_sel_hi:[1,0]
	v_pk_mul_f32 v[238:239], v[90:91], v[230:231] op_sel_hi:[1,0]
	v_mul_f32_e32 v236, 0xbfb8aa3b, v236
	v_mul_f32_e32 v237, 0xbfb8aa3b, v237
	v_mul_f32_e32 v238, 0xbfb8aa3b, v238
	v_mul_f32_e32 v239, 0xbfb8aa3b, v239
	v_exp_f32_e32 v236, v236
	v_exp_f32_e32 v237, v237
	v_exp_f32_e32 v238, v238
	v_exp_f32_e32 v239, v239
	v_add_f32_e32 v236, 1.0, v236
	v_add_f32_e32 v237, 1.0, v237
	v_add_f32_e32 v238, 1.0, v238
	v_add_f32_e32 v239, 1.0, v239
	v_rcp_f32_e32 v236, v236
	v_rcp_f32_e32 v237, v237
	v_rcp_f32_e32 v238, v238
	v_rcp_f32_e32 v239, v239
	v_lshlrev_b32_e32 v232, 16, v214
	v_and_b32_e32 v233, 0xffff0000, v214
	v_lshlrev_b32_e32 v234, 16, v215
	v_and_b32_e32 v235, 0xffff0000, v215
	v_pk_fma_f32 v[88:89], v[236:237], v[232:233], v[182:183]
	v_pk_fma_f32 v[90:91], v[238:239], v[234:235], v[184:185]
	v_pk_mul_f32 v[236:237], v[88:89], v[88:89]
	v_pk_mul_f32 v[238:239], v[90:91], v[90:91]
	v_add_f32_e32 v229, v229, v236
	v_add_f32_e32 v229, v229, v237
	v_add_f32_e32 v229, v229, v238
	v_add_f32_e32 v229, v229, v239
	v_pk_mul_f32 v[236:237], v[84:85], v[230:231] op_sel_hi:[1,0]
	v_pk_mul_f32 v[238:239], v[86:87], v[230:231] op_sel_hi:[1,0]
	v_mul_f32_e32 v236, 0xbfb8aa3b, v236
	v_mul_f32_e32 v237, 0xbfb8aa3b, v237
	v_mul_f32_e32 v238, 0xbfb8aa3b, v238
	v_mul_f32_e32 v239, 0xbfb8aa3b, v239
	v_exp_f32_e32 v236, v236
	v_exp_f32_e32 v237, v237
	v_exp_f32_e32 v238, v238
	v_exp_f32_e32 v239, v239
	v_add_f32_e32 v236, 1.0, v236
	v_add_f32_e32 v237, 1.0, v237
	v_add_f32_e32 v238, 1.0, v238
	v_add_f32_e32 v239, 1.0, v239
	v_rcp_f32_e32 v236, v236
	v_rcp_f32_e32 v237, v237
	v_rcp_f32_e32 v238, v238
	v_rcp_f32_e32 v239, v239
	v_lshlrev_b32_e32 v232, 16, v216
	v_and_b32_e32 v233, 0xffff0000, v216
	v_lshlrev_b32_e32 v234, 16, v217
	v_and_b32_e32 v235, 0xffff0000, v217
	v_pk_fma_f32 v[84:85], v[236:237], v[232:233], v[186:187]
	v_pk_fma_f32 v[86:87], v[238:239], v[234:235], v[188:189]
	v_pk_mul_f32 v[236:237], v[84:85], v[84:85]
	v_pk_mul_f32 v[238:239], v[86:87], v[86:87]
	v_add_f32_e32 v229, v229, v236
	v_add_f32_e32 v229, v229, v237
	v_add_f32_e32 v229, v229, v238
	v_add_f32_e32 v229, v229, v239
	v_pk_mul_f32 v[236:237], v[80:81], v[230:231] op_sel_hi:[1,0]
	v_pk_mul_f32 v[238:239], v[82:83], v[230:231] op_sel_hi:[1,0]
	v_mul_f32_e32 v236, 0xbfb8aa3b, v236
	v_mul_f32_e32 v237, 0xbfb8aa3b, v237
	v_mul_f32_e32 v238, 0xbfb8aa3b, v238
	v_mul_f32_e32 v239, 0xbfb8aa3b, v239
	v_exp_f32_e32 v236, v236
	v_exp_f32_e32 v237, v237
	v_exp_f32_e32 v238, v238
	v_exp_f32_e32 v239, v239
	v_add_f32_e32 v236, 1.0, v236
	v_add_f32_e32 v237, 1.0, v237
	v_add_f32_e32 v238, 1.0, v238
	v_add_f32_e32 v239, 1.0, v239
	v_rcp_f32_e32 v236, v236
	v_rcp_f32_e32 v237, v237
	v_rcp_f32_e32 v238, v238
	v_rcp_f32_e32 v239, v239
	v_lshlrev_b32_e32 v232, 16, v218
	v_and_b32_e32 v233, 0xffff0000, v218
	v_lshlrev_b32_e32 v234, 16, v219
	v_and_b32_e32 v235, 0xffff0000, v219
	v_pk_fma_f32 v[80:81], v[236:237], v[232:233], v[190:191]
	v_pk_fma_f32 v[82:83], v[238:239], v[234:235], v[192:193]
	v_pk_mul_f32 v[236:237], v[80:81], v[80:81]
	v_pk_mul_f32 v[238:239], v[82:83], v[82:83]
	v_add_f32_e32 v229, v229, v236
	v_add_f32_e32 v229, v229, v237
	v_add_f32_e32 v229, v229, v238
	v_add_f32_e32 v229, v229, v239
	v_xor_b32_e32 v232, 64, v224
	ds_bpermute_b32 v233, v232, v229
	s_waitcnt lgkmcnt(0)
	v_add_f32_e32 v229, v229, v233
	v_xor_b32_e32 v232, 0x80, v224
	ds_bpermute_b32 v233, v232, v229
	s_waitcnt lgkmcnt(0)
	v_add_f32_e32 v229, v229, v233
	s_and_saveexec_b64 s[100:101], s[98:99]
	global_atomic_add_f32 v226, v229, s[16:17] offset:128
	s_mov_b64 exec, s[100:101]
	s_waitcnt vmcnt(17)
; __device__ __forceinline__ float bf_lo(unsigned w) { return __uint_as_float(w << 16); }
; __device__ __forceinline__ float bf_hi(unsigned w) { return __uint_as_float(w & 0xffff0000u); }
; __device__ __forceinline__ float sigmoidf_(float x) { return __builtin_amdgcn_rcpf(1.0f + __expf(-x)); }
; __device__ __forceinline__ float rinv_of(float ssq) { return rsqrtf(ssq * (1.0f / 1024.0f) + EPS); }
; __device__ __forceinline__ u32x4 pack8(const f32x4 a, const f32x4 b) { u32x4 w; w.x = cvt_pk_bf16(a[0], a[1]); w.y = cvt_pk_bf16(a[2], a[3]); w.z = cvt_pk_bf16(b[0], b[1]); w.w = cvt_pk_bf16(b[2], b[3]); return w; }
;     __device__ __forceinline__ void operator()(const AccT& acc, const pg8::Unit& u, int wr, int wc, int fr, int fq) const {
;     ...
;                 for (int mm = 0; mm < 2; ++mm) { const int r = EPI_ROW(u, ai, 2 * mp + mm); rs[mm] = ssq_in[r];
; #pragma unroll
;                     for (int bj = 0; bj < 2; ++bj) { const int c = EPI_COL(u, bj); const float* hp = h + (size_t)r * D + c; hv[mm][bj][0] = *(const f32x4*)hp; hv[mm][bj][1] = *(const f32x4*)(hp + 4); pw[mm][bj] = *(const u32x4*)(pp + (size_t)r * D + c); } }
; #pragma unroll
;                 for (int mm = 0; mm < 2; ++mm) { const int m = 2 * mp + mm, r = EPI_ROW(u, ai, m); float s = 0.f; const float ri = rinv_of(rs[mm]);
; #pragma unroll
;                     for (int bj = 0; bj < 2; ++bj) { const int c = EPI_COL(u, bj); float* hp = h + (size_t)r * D + c; const u32x4 p4 = pw[mm][bj];
;                         const f32x4 a0 = acc[ai][bj][m][0] * ri, a1 = acc[ai][bj][m][1] * ri; f32x4 v0 = hv[mm][bj][0], v1 = hv[mm][bj][1];
;                         v0[0] += mul * sigmoidf_(a0[0]) * bf_lo(p4.x); v0[1] += mul * sigmoidf_(a0[1]) * bf_hi(p4.x); v0[2] += mul * sigmoidf_(a0[2]) * bf_lo(p4.y); v0[3] += mul * sigmoidf_(a0[3]) * bf_hi(p4.y);
;                         v1[0] += mul * sigmoidf_(a1[0]) * bf_lo(p4.z); v1[1] += mul * sigmoidf_(a1[1]) * bf_hi(p4.z); v1[2] += mul * sigmoidf_(a1[2]) * bf_lo(p4.w); v1[3] += mul * sigmoidf_(a1[3]) * bf_hi(p4.w);
;                         *(f32x4*)hp = v0; *(f32x4*)(hp + 4) = v1;
;                         if (hb) *(u32x4*)(hb + (size_t)r * D + c) = pack8(v0, v1);
;                         s += sq8(v0, v1); }
;                     ssq_commit(s, ssq, r, fq); }
	v_fmamk_f32 v230, v228, 0x3a800000, v225
	v_rsq_f32_e32 v230, v230
	v_mov_b32_e32 v229, 0
	v_pk_mul_f32 v[236:237], v[76:77], v[230:231] op_sel_hi:[1,0]
	v_pk_mul_f32 v[238:239], v[78:79], v[230:231] op_sel_hi:[1,0]
	v_mul_f32_e32 v236, 0xbfb8aa3b, v236
	v_mul_f32_e32 v237, 0xbfb8aa3b, v237
	v_mul_f32_e32 v238, 0xbfb8aa3b, v238
	v_mul_f32_e32 v239, 0xbfb8aa3b, v239
	v_exp_f32_e32 v236, v236
	v_exp_f32_e32 v237, v237
	v_exp_f32_e32 v238, v238
	v_exp_f32_e32 v239, v239
	v_add_f32_e32 v236, 1.0, v236
	v_add_f32_e32 v237, 1.0, v237
	v_add_f32_e32 v238, 1.0, v238
	v_add_f32_e32 v239, 1.0, v239
	v_rcp_f32_e32 v236, v236
	v_rcp_f32_e32 v237, v237
	v_rcp_f32_e32 v238, v238
	v_rcp_f32_e32 v239, v239
	v_lshlrev_b32_e32 v232, 16, v220
	v_and_b32_e32 v233, 0xffff0000, v220
	v_lshlrev_b32_e32 v234, 16, v221
	v_and_b32_e32 v235, 0xffff0000, v221
	v_pk_fma_f32 v[76:77], v[236:237], v[232:233], v[194:195]
	v_pk_fma_f32 v[78:79], v[238:239], v[234:235], v[196:197]
	v_pk_mul_f32 v[236:237], v[76:77], v[76:77]
	v_pk_mul_f32 v[238:239], v[78:79], v[78:79]
	v_add_f32_e32 v229, v229, v236
	v_add_f32_e32 v229, v229, v237
	v_add_f32_e32 v229, v229, v238
	v_add_f32_e32 v229, v229, v239
	v_pk_mul_f32 v[236:237], v[72:73], v[230:231] op_sel_hi:[1,0]
	v_pk_mul_f32 v[238:239], v[74:75], v[230:231] op_sel_hi:[1,0]
	v_mul_f32_e32 v236, 0xbfb8aa3b, v236
	v_mul_f32_e32 v237, 0xbfb8aa3b, v237
	v_mul_f32_e32 v238, 0xbfb8aa3b, v238
	v_mul_f32_e32 v239, 0xbfb8aa3b, v239
	v_exp_f32_e32 v236, v236
	v_exp_f32_e32 v237, v237
	v_exp_f32_e32 v238, v238
	v_exp_f32_e32 v239, v239
	v_add_f32_e32 v236, 1.0, v236
	v_add_f32_e32 v237, 1.0, v237
	v_add_f32_e32 v238, 1.0, v238
	v_add_f32_e32 v239, 1.0, v239
	v_rcp_f32_e32 v236, v236
	v_rcp_f32_e32 v237, v237
	v_rcp_f32_e32 v238, v238
	v_rcp_f32_e32 v239, v239
	v_lshlrev_b32_e32 v232, 16, v222
	v_and_b32_e32 v233, 0xffff0000, v222
	v_lshlrev_b32_e32 v234, 16, v223
	v_and_b32_e32 v235, 0xffff0000, v223
	v_pk_fma_f32 v[72:73], v[236:237], v[232:233], v[198:199]
	v_pk_fma_f32 v[74:75], v[238:239], v[234:235], v[200:201]
	v_pk_mul_f32 v[236:237], v[72:73], v[72:73]
	v_pk_mul_f32 v[238:239], v[74:75], v[74:75]
	v_add_f32_e32 v229, v229, v236
	v_add_f32_e32 v229, v229, v237
	v_add_f32_e32 v229, v229, v238
	v_add_f32_e32 v229, v229, v239
	v_pk_mul_f32 v[236:237], v[68:69], v[230:231] op_sel_hi:[1,0]
	v_pk_mul_f32 v[238:239], v[70:71], v[230:231] op_sel_hi:[1,0]
	v_mul_f32_e32 v236, 0xbfb8aa3b, v236
	v_mul_f32_e32 v237, 0xbfb8aa3b, v237
	v_mul_f32_e32 v238, 0xbfb8aa3b, v238
	v_mul_f32_e32 v239, 0xbfb8aa3b, v239
	v_exp_f32_e32 v236, v236
	v_exp_f32_e32 v237, v237
	v_exp_f32_e32 v238, v238
	v_exp_f32_e32 v239, v239
	v_add_f32_e32 v236, 1.0, v236
	v_add_f32_e32 v237, 1.0, v237
	v_add_f32_e32 v238, 1.0, v238
	v_add_f32_e32 v239, 1.0, v239
	v_rcp_f32_e32 v236, v236
	v_rcp_f32_e32 v237, v237
	v_rcp_f32_e32 v238, v238
	v_rcp_f32_e32 v239, v239
	v_lshlrev_b32_e32 v232, 16, v244
	v_and_b32_e32 v233, 0xffff0000, v244
	v_lshlrev_b32_e32 v234, 16, v245
	v_and_b32_e32 v235, 0xffff0000, v245
	v_pk_fma_f32 v[68:69], v[236:237], v[232:233], v[202:203]
	v_pk_fma_f32 v[70:71], v[238:239], v[234:235], v[204:205]
	v_pk_mul_f32 v[236:237], v[68:69], v[68:69]
	v_pk_mul_f32 v[238:239], v[70:71], v[70:71]
	v_add_f32_e32 v229, v229, v236
	v_add_f32_e32 v229, v229, v237
	v_add_f32_e32 v229, v229, v238
	v_add_f32_e32 v229, v229, v239
	v_pk_mul_f32 v[236:237], v[64:65], v[230:231] op_sel_hi:[1,0]
	v_pk_mul_f32 v[238:239], v[66:67], v[230:231] op_sel_hi:[1,0]
	v_mul_f32_e32 v236, 0xbfb8aa3b, v236
	v_mul_f32_e32 v237, 0xbfb8aa3b, v237
	v_mul_f32_e32 v238, 0xbfb8aa3b, v238
	v_mul_f32_e32 v239, 0xbfb8aa3b, v239
	v_exp_f32_e32 v236, v236
	v_exp_f32_e32 v237, v237
	v_exp_f32_e32 v238, v238
	v_exp_f32_e32 v239, v239
	v_add_f32_e32 v236, 1.0, v236
	v_add_f32_e32 v237, 1.0, v237
	v_add_f32_e32 v238, 1.0, v238
	v_add_f32_e32 v239, 1.0, v239
	v_rcp_f32_e32 v236, v236
	v_rcp_f32_e32 v237, v237
	v_rcp_f32_e32 v238, v238
	v_rcp_f32_e32 v239, v239
	v_lshlrev_b32_e32 v232, 16, v246
	v_and_b32_e32 v233, 0xffff0000, v246
	v_lshlrev_b32_e32 v234, 16, v247
	v_and_b32_e32 v235, 0xffff0000, v247
	v_pk_fma_f32 v[64:65], v[236:237], v[232:233], v[206:207]
	v_pk_fma_f32 v[66:67], v[238:239], v[234:235], v[208:209]
	v_pk_mul_f32 v[236:237], v[64:65], v[64:65]
	v_pk_mul_f32 v[238:239], v[66:67], v[66:67]
	v_add_f32_e32 v229, v229, v236
	v_add_f32_e32 v229, v229, v237
	v_add_f32_e32 v229, v229, v238
	v_add_f32_e32 v229, v229, v239
	v_xor_b32_e32 v232, 64, v224
	ds_bpermute_b32 v233, v232, v229
	s_waitcnt lgkmcnt(0)
	v_add_f32_e32 v229, v229, v233
	v_xor_b32_e32 v232, 0x80, v224
	ds_bpermute_b32 v233, v232, v229
	s_waitcnt lgkmcnt(0)
	v_add_f32_e32 v229, v229, v233
	s_and_saveexec_b64 s[100:101], s[98:99]
	global_atomic_add_f32 v226, v229, s[16:17] offset:192
	s_mov_b64 exec, s[100:101]
	v_add_u32_e32 v232, 0xa0000, v243
	v_lshrrev_b32_e32 v233, 1, v232
	global_load_dword v227, v226, s[14:15] offset:640
	global_load_dwordx4 v[178:181], v232, s[52:53]
	global_load_dwordx4 v[182:185], v232, s[52:53] offset:16
	global_load_dwordx4 v[186:189], v232, s[52:53] offset:512
	global_load_dwordx4 v[190:193], v232, s[52:53] offset:528
	global_load_dwordx4 v[212:215], v233, s[72:73]
	global_load_dwordx4 v[216:219], v233, s[72:73] offset:256
	v_add_u32_e32 v232, 0xb0000, v243
	v_lshrrev_b32_e32 v233, 1, v232
	global_load_dword v228, v226, s[14:15] offset:704
	global_load_dwordx4 v[194:197], v232, s[52:53]
	global_load_dwordx4 v[198:201], v232, s[52:53] offset:16
	global_load_dwordx4 v[202:205], v232, s[52:53] offset:512
	global_load_dwordx4 v[206:209], v232, s[52:53] offset:528
	global_load_dwordx4 v[220:223], v233, s[72:73]
	global_load_dwordx4 v[244:247], v233, s[72:73] offset:256
	s_waitcnt vmcnt(23)
; __device__ __forceinline__ float bf_lo(unsigned w) { return __uint_as_float(w << 16); }
; __device__ __forceinline__ float bf_hi(unsigned w) { return __uint_as_float(w & 0xffff0000u); }
; __device__ __forceinline__ float sigmoidf_(float x) { return __builtin_amdgcn_rcpf(1.0f + __expf(-x)); }
; __device__ __forceinline__ float rinv_of(float ssq) { return rsqrtf(ssq * (1.0f / 1024.0f) + EPS); }
; __device__ __forceinline__ u32x4 pack8(const f32x4 a, const f32x4 b) { u32x4 w; w.x = cvt_pk_bf16(a[0], a[1]); w.y = cvt_pk_bf16(a[2], a[3]); w.z = cvt_pk_bf16(b[0], b[1]); w.w = cvt_pk_bf16(b[2], b[3]); return w; }
;     __device__ __forceinline__ void operator()(const AccT& acc, const pg8::Unit& u, int wr, int wc, int fr, int fq) const {
;     ...
;                 for (int mm = 0; mm < 2; ++mm) { const int r = EPI_ROW(u, ai, 2 * mp + mm); rs[mm] = ssq_in[r];
; #pragma unroll
;                     for (int bj = 0; bj < 2; ++bj) { const int c = EPI_COL(u, bj); const float* hp = h + (size_t)r * D + c; hv[mm][bj][0] = *(const f32x4*)hp; hv[mm][bj][1] = *(const f32x4*)(hp + 4); pw[mm][bj] = *(const u32x4*)(pp + (size_t)r * D + c); } }
; #pragma unroll
;                 for (int mm = 0; mm < 2; ++mm) { const int m = 2 * mp + mm, r = EPI_ROW(u, ai, m); float s = 0.f; const float ri = rinv_of(rs[mm]);
; #pragma unroll
;                     for (int bj = 0; bj < 2; ++bj) { const int c = EPI_COL(u, bj); float* hp = h + (size_t)r * D + c; const u32x4 p4 = pw[mm][bj];
;                         const f32x4 a0 = acc[ai][bj][m][0] * ri, a1 = acc[ai][bj][m][1] * ri; f32x4 v0 = hv[mm][bj][0], v1 = hv[mm][bj][1];
;                         v0[0] += mul * sigmoidf_(a0[0]) * bf_lo(p4.x); v0[1] += mul * sigmoidf_(a0[1]) * bf_hi(p4.x); v0[2] += mul * sigmoidf_(a0[2]) * bf_lo(p4.y); v0[3] += mul * sigmoidf_(a0[3]) * bf_hi(p4.y);
;                         v1[0] += mul * sigmoidf_(a1[0]) * bf_lo(p4.z); v1[1] += mul * sigmoidf_(a1[1]) * bf_hi(p4.z); v1[2] += mul * sigmoidf_(a1[2]) * bf_lo(p4.w); v1[3] += mul * sigmoidf_(a1[3]) * bf_hi(p4.w);
;                         *(f32x4*)hp = v0; *(f32x4*)(hp + 4) = v1;
;                         if (hb) *(u32x4*)(hb + (size_t)r * D + c) = pack8(v0, v1);
;                         s += sq8(v0, v1); }
;                     ssq_commit(s, ssq, r, fq); }
	v_fmamk_f32 v230, v176, 0x3a800000, v225
	v_rsq_f32_e32 v230, v230
	v_mov_b32_e32 v229, 0
	v_pk_mul_f32 v[236:237], v[60:61], v[230:231] op_sel_hi:[1,0]
	v_pk_mul_f32 v[238:239], v[62:63], v[230:231] op_sel_hi:[1,0]
	v_mul_f32_e32 v236, 0xbfb8aa3b, v236
	v_mul_f32_e32 v237, 0xbfb8aa3b, v237
	v_mul_f32_e32 v238, 0xbfb8aa3b, v238
	v_mul_f32_e32 v239, 0xbfb8aa3b, v239
	v_exp_f32_e32 v236, v236
	v_exp_f32_e32 v237, v237
	v_exp_f32_e32 v238, v238
	v_exp_f32_e32 v239, v239
	v_add_f32_e32 v236, 1.0, v236
	v_add_f32_e32 v237, 1.0, v237
	v_add_f32_e32 v238, 1.0, v238
	v_add_f32_e32 v239, 1.0, v239
	v_rcp_f32_e32 v236, v236
	v_rcp_f32_e32 v237, v237
	v_rcp_f32_e32 v238, v238
	v_rcp_f32_e32 v239, v239
	v_lshlrev_b32_e32 v232, 16, v144
	v_and_b32_e32 v233, 0xffff0000, v144
	v_lshlrev_b32_e32 v234, 16, v145
	v_and_b32_e32 v235, 0xffff0000, v145
	v_pk_fma_f32 v[60:61], v[236:237], v[232:233], v[128:129]
	v_pk_fma_f32 v[62:63], v[238:239], v[234:235], v[130:131]
	v_pk_mul_f32 v[236:237], v[60:61], v[60:61]
	v_pk_mul_f32 v[238:239], v[62:63], v[62:63]
	v_add_f32_e32 v229, v229, v236
	v_add_f32_e32 v229, v229, v237
	v_add_f32_e32 v229, v229, v238
	v_add_f32_e32 v229, v229, v239
	v_pk_mul_f32 v[236:237], v[56:57], v[230:231] op_sel_hi:[1,0]
	v_pk_mul_f32 v[238:239], v[58:59], v[230:231] op_sel_hi:[1,0]
	v_mul_f32_e32 v236, 0xbfb8aa3b, v236
	v_mul_f32_e32 v237, 0xbfb8aa3b, v237
	v_mul_f32_e32 v238, 0xbfb8aa3b, v238
	v_mul_f32_e32 v239, 0xbfb8aa3b, v239
	v_exp_f32_e32 v236, v236
	v_exp_f32_e32 v237, v237
	v_exp_f32_e32 v238, v238
	v_exp_f32_e32 v239, v239
	v_add_f32_e32 v236, 1.0, v236
	v_add_f32_e32 v237, 1.0, v237
	v_add_f32_e32 v238, 1.0, v238
	v_add_f32_e32 v239, 1.0, v239
	v_rcp_f32_e32 v236, v236
	v_rcp_f32_e32 v237, v237
	v_rcp_f32_e32 v238, v238
	v_rcp_f32_e32 v239, v239
	v_lshlrev_b32_e32 v232, 16, v146
	v_and_b32_e32 v233, 0xffff0000, v146
	v_lshlrev_b32_e32 v234, 16, v147
	v_and_b32_e32 v235, 0xffff0000, v147
	v_pk_fma_f32 v[56:57], v[236:237], v[232:233], v[132:133]
	v_pk_fma_f32 v[58:59], v[238:239], v[234:235], v[134:135]
	v_pk_mul_f32 v[236:237], v[56:57], v[56:57]
	v_pk_mul_f32 v[238:239], v[58:59], v[58:59]
	v_add_f32_e32 v229, v229, v236
	v_add_f32_e32 v229, v229, v237
	v_add_f32_e32 v229, v229, v238
	v_add_f32_e32 v229, v229, v239
	v_pk_mul_f32 v[236:237], v[52:53], v[230:231] op_sel_hi:[1,0]
	v_pk_mul_f32 v[238:239], v[54:55], v[230:231] op_sel_hi:[1,0]
	v_mul_f32_e32 v236, 0xbfb8aa3b, v236
	v_mul_f32_e32 v237, 0xbfb8aa3b, v237
	v_mul_f32_e32 v238, 0xbfb8aa3b, v238
	v_mul_f32_e32 v239, 0xbfb8aa3b, v239
	v_exp_f32_e32 v236, v236
	v_exp_f32_e32 v237, v237
	v_exp_f32_e32 v238, v238
	v_exp_f32_e32 v239, v239
	v_add_f32_e32 v236, 1.0, v236
	v_add_f32_e32 v237, 1.0, v237
	v_add_f32_e32 v238, 1.0, v238
	v_add_f32_e32 v239, 1.0, v239
	v_rcp_f32_e32 v236, v236
	v_rcp_f32_e32 v237, v237
	v_rcp_f32_e32 v238, v238
	v_rcp_f32_e32 v239, v239
	v_lshlrev_b32_e32 v232, 16, v148
	v_and_b32_e32 v233, 0xffff0000, v148
	v_lshlrev_b32_e32 v234, 16, v149
	v_and_b32_e32 v235, 0xffff0000, v149
	v_pk_fma_f32 v[52:53], v[236:237], v[232:233], v[136:137]
	v_pk_fma_f32 v[54:55], v[238:239], v[234:235], v[138:139]
	v_pk_mul_f32 v[236:237], v[52:53], v[52:53]
	v_pk_mul_f32 v[238:239], v[54:55], v[54:55]
	v_add_f32_e32 v229, v229, v236
	v_add_f32_e32 v229, v229, v237
	v_add_f32_e32 v229, v229, v238
	v_add_f32_e32 v229, v229, v239
	v_pk_mul_f32 v[236:237], v[48:49], v[230:231] op_sel_hi:[1,0]
	v_pk_mul_f32 v[238:239], v[50:51], v[230:231] op_sel_hi:[1,0]
	v_mul_f32_e32 v236, 0xbfb8aa3b, v236
	v_mul_f32_e32 v237, 0xbfb8aa3b, v237
	v_mul_f32_e32 v238, 0xbfb8aa3b, v238
	v_mul_f32_e32 v239, 0xbfb8aa3b, v239
	v_exp_f32_e32 v236, v236
	v_exp_f32_e32 v237, v237
	v_exp_f32_e32 v238, v238
	v_exp_f32_e32 v239, v239
	v_add_f32_e32 v236, 1.0, v236
	v_add_f32_e32 v237, 1.0, v237
	v_add_f32_e32 v238, 1.0, v238
	v_add_f32_e32 v239, 1.0, v239
	v_rcp_f32_e32 v236, v236
	v_rcp_f32_e32 v237, v237
	v_rcp_f32_e32 v238, v238
	v_rcp_f32_e32 v239, v239
	v_lshlrev_b32_e32 v232, 16, v150
	v_and_b32_e32 v233, 0xffff0000, v150
	v_lshlrev_b32_e32 v234, 16, v151
	v_and_b32_e32 v235, 0xffff0000, v151
	v_pk_fma_f32 v[48:49], v[236:237], v[232:233], v[140:141]
	v_pk_fma_f32 v[50:51], v[238:239], v[234:235], v[142:143]
	v_pk_mul_f32 v[236:237], v[48:49], v[48:49]
	v_pk_mul_f32 v[238:239], v[50:51], v[50:51]
	v_add_f32_e32 v229, v229, v236
	v_add_f32_e32 v229, v229, v237
	v_add_f32_e32 v229, v229, v238
	v_add_f32_e32 v229, v229, v239
	v_xor_b32_e32 v232, 64, v224
	ds_bpermute_b32 v233, v232, v229
	s_waitcnt lgkmcnt(0)
	v_add_f32_e32 v229, v229, v233
	v_xor_b32_e32 v232, 0x80, v224
	ds_bpermute_b32 v233, v232, v229
	s_waitcnt lgkmcnt(0)
	v_add_f32_e32 v229, v229, v233
	s_and_saveexec_b64 s[100:101], s[98:99]
	global_atomic_add_f32 v226, v229, s[16:17] offset:512
	s_mov_b64 exec, s[100:101]
	s_waitcnt vmcnt(17)
; __device__ __forceinline__ float bf_lo(unsigned w) { return __uint_as_float(w << 16); }
; __device__ __forceinline__ float bf_hi(unsigned w) { return __uint_as_float(w & 0xffff0000u); }
; __device__ __forceinline__ float sigmoidf_(float x) { return __builtin_amdgcn_rcpf(1.0f + __expf(-x)); }
; __device__ __forceinline__ float rinv_of(float ssq) { return rsqrtf(ssq * (1.0f / 1024.0f) + EPS); }
; __device__ __forceinline__ u32x4 pack8(const f32x4 a, const f32x4 b) { u32x4 w; w.x = cvt_pk_bf16(a[0], a[1]); w.y = cvt_pk_bf16(a[2], a[3]); w.z = cvt_pk_bf16(b[0], b[1]); w.w = cvt_pk_bf16(b[2], b[3]); return w; }
;     __device__ __forceinline__ void operator()(const AccT& acc, const pg8::Unit& u, int wr, int wc, int fr, int fq) const {
;     ...
;                 for (int mm = 0; mm < 2; ++mm) { const int r = EPI_ROW(u, ai, 2 * mp + mm); rs[mm] = ssq_in[r];
; #pragma unroll
;                     for (int bj = 0; bj < 2; ++bj) { const int c = EPI_COL(u, bj); const float* hp = h + (size_t)r * D + c; hv[mm][bj][0] = *(const f32x4*)hp; hv[mm][bj][1] = *(const f32x4*)(hp + 4); pw[mm][bj] = *(const u32x4*)(pp + (size_t)r * D + c); } }
; #pragma unroll
;                 for (int mm = 0; mm < 2; ++mm) { const int m = 2 * mp + mm, r = EPI_ROW(u, ai, m); float s = 0.f; const float ri = rinv_of(rs[mm]);
; #pragma unroll
;                     for (int bj = 0; bj < 2; ++bj) { const int c = EPI_COL(u, bj); float* hp = h + (size_t)r * D + c; const u32x4 p4 = pw[mm][bj];
;                         const f32x4 a0 = acc[ai][bj][m][0] * ri, a1 = acc[ai][bj][m][1] * ri; f32x4 v0 = hv[mm][bj][0], v1 = hv[mm][bj][1];
;                         v0[0] += mul * sigmoidf_(a0[0]) * bf_lo(p4.x); v0[1] += mul * sigmoidf_(a0[1]) * bf_hi(p4.x); v0[2] += mul * sigmoidf_(a0[2]) * bf_lo(p4.y); v0[3] += mul * sigmoidf_(a0[3]) * bf_hi(p4.y);
;                         v1[0] += mul * sigmoidf_(a1[0]) * bf_lo(p4.z); v1[1] += mul * sigmoidf_(a1[1]) * bf_hi(p4.z); v1[2] += mul * sigmoidf_(a1[2]) * bf_lo(p4.w); v1[3] += mul * sigmoidf_(a1[3]) * bf_hi(p4.w);
;                         *(f32x4*)hp = v0; *(f32x4*)(hp + 4) = v1;
;                         if (hb) *(u32x4*)(hb + (size_t)r * D + c) = pack8(v0, v1);
;                         s += sq8(v0, v1); }
;                     ssq_commit(s, ssq, r, fq); }
	v_fmamk_f32 v230, v177, 0x3a800000, v225
	v_rsq_f32_e32 v230, v230
	v_mov_b32_e32 v229, 0
	v_pk_mul_f32 v[236:237], v[44:45], v[230:231] op_sel_hi:[1,0]
	v_pk_mul_f32 v[238:239], v[46:47], v[230:231] op_sel_hi:[1,0]
	v_mul_f32_e32 v236, 0xbfb8aa3b, v236
	v_mul_f32_e32 v237, 0xbfb8aa3b, v237
	v_mul_f32_e32 v238, 0xbfb8aa3b, v238
	v_mul_f32_e32 v239, 0xbfb8aa3b, v239
	v_exp_f32_e32 v236, v236
	v_exp_f32_e32 v237, v237
	v_exp_f32_e32 v238, v238
	v_exp_f32_e32 v239, v239
	v_add_f32_e32 v236, 1.0, v236
	v_add_f32_e32 v237, 1.0, v237
	v_add_f32_e32 v238, 1.0, v238
	v_add_f32_e32 v239, 1.0, v239
	v_rcp_f32_e32 v236, v236
	v_rcp_f32_e32 v237, v237
	v_rcp_f32_e32 v238, v238
	v_rcp_f32_e32 v239, v239
	v_lshlrev_b32_e32 v232, 16, v168
	v_and_b32_e32 v233, 0xffff0000, v168
	v_lshlrev_b32_e32 v234, 16, v169
	v_and_b32_e32 v235, 0xffff0000, v169
	v_pk_fma_f32 v[44:45], v[236:237], v[232:233], v[152:153]
	v_pk_fma_f32 v[46:47], v[238:239], v[234:235], v[154:155]
	v_pk_mul_f32 v[236:237], v[44:45], v[44:45]
	v_pk_mul_f32 v[238:239], v[46:47], v[46:47]
	v_add_f32_e32 v229, v229, v236
	v_add_f32_e32 v229, v229, v237
	v_add_f32_e32 v229, v229, v238
	v_add_f32_e32 v229, v229, v239
	v_pk_mul_f32 v[236:237], v[40:41], v[230:231] op_sel_hi:[1,0]
	v_pk_mul_f32 v[238:239], v[42:43], v[230:231] op_sel_hi:[1,0]
	v_mul_f32_e32 v236, 0xbfb8aa3b, v236
	v_mul_f32_e32 v237, 0xbfb8aa3b, v237
	v_mul_f32_e32 v238, 0xbfb8aa3b, v238
	v_mul_f32_e32 v239, 0xbfb8aa3b, v239
	v_exp_f32_e32 v236, v236
	v_exp_f32_e32 v237, v237
	v_exp_f32_e32 v238, v238
	v_exp_f32_e32 v239, v239
	v_add_f32_e32 v236, 1.0, v236
	v_add_f32_e32 v237, 1.0, v237
	v_add_f32_e32 v238, 1.0, v238
	v_add_f32_e32 v239, 1.0, v239
	v_rcp_f32_e32 v236, v236
	v_rcp_f32_e32 v237, v237
	v_rcp_f32_e32 v238, v238
	v_rcp_f32_e32 v239, v239
	v_lshlrev_b32_e32 v232, 16, v170
	v_and_b32_e32 v233, 0xffff0000, v170
	v_lshlrev_b32_e32 v234, 16, v171
	v_and_b32_e32 v235, 0xffff0000, v171
	v_pk_fma_f32 v[40:41], v[236:237], v[232:233], v[156:157]
	v_pk_fma_f32 v[42:43], v[238:239], v[234:235], v[158:159]
	v_pk_mul_f32 v[236:237], v[40:41], v[40:41]
	v_pk_mul_f32 v[238:239], v[42:43], v[42:43]
	v_add_f32_e32 v229, v229, v236
	v_add_f32_e32 v229, v229, v237
	v_add_f32_e32 v229, v229, v238
	v_add_f32_e32 v229, v229, v239
	v_pk_mul_f32 v[236:237], v[36:37], v[230:231] op_sel_hi:[1,0]
	v_pk_mul_f32 v[238:239], v[38:39], v[230:231] op_sel_hi:[1,0]
	v_mul_f32_e32 v236, 0xbfb8aa3b, v236
	v_mul_f32_e32 v237, 0xbfb8aa3b, v237
	v_mul_f32_e32 v238, 0xbfb8aa3b, v238
	v_mul_f32_e32 v239, 0xbfb8aa3b, v239
	v_exp_f32_e32 v236, v236
	v_exp_f32_e32 v237, v237
	v_exp_f32_e32 v238, v238
	v_exp_f32_e32 v239, v239
	v_add_f32_e32 v236, 1.0, v236
	v_add_f32_e32 v237, 1.0, v237
	v_add_f32_e32 v238, 1.0, v238
	v_add_f32_e32 v239, 1.0, v239
	v_rcp_f32_e32 v236, v236
	v_rcp_f32_e32 v237, v237
	v_rcp_f32_e32 v238, v238
	v_rcp_f32_e32 v239, v239
	v_lshlrev_b32_e32 v232, 16, v172
	v_and_b32_e32 v233, 0xffff0000, v172
	v_lshlrev_b32_e32 v234, 16, v173
	v_and_b32_e32 v235, 0xffff0000, v173
	v_pk_fma_f32 v[36:37], v[236:237], v[232:233], v[160:161]
	v_pk_fma_f32 v[38:39], v[238:239], v[234:235], v[162:163]
	v_pk_mul_f32 v[236:237], v[36:37], v[36:37]
	v_pk_mul_f32 v[238:239], v[38:39], v[38:39]
	v_add_f32_e32 v229, v229, v236
	v_add_f32_e32 v229, v229, v237
	v_add_f32_e32 v229, v229, v238
	v_add_f32_e32 v229, v229, v239
	v_pk_mul_f32 v[236:237], v[32:33], v[230:231] op_sel_hi:[1,0]
	v_pk_mul_f32 v[238:239], v[34:35], v[230:231] op_sel_hi:[1,0]
	v_mul_f32_e32 v236, 0xbfb8aa3b, v236
	v_mul_f32_e32 v237, 0xbfb8aa3b, v237
	v_mul_f32_e32 v238, 0xbfb8aa3b, v238
	v_mul_f32_e32 v239, 0xbfb8aa3b, v239
	v_exp_f32_e32 v236, v236
	v_exp_f32_e32 v237, v237
	v_exp_f32_e32 v238, v238
	v_exp_f32_e32 v239, v239
	v_add_f32_e32 v236, 1.0, v236
	v_add_f32_e32 v237, 1.0, v237
	v_add_f32_e32 v238, 1.0, v238
	v_add_f32_e32 v239, 1.0, v239
	v_rcp_f32_e32 v236, v236
	v_rcp_f32_e32 v237, v237
	v_rcp_f32_e32 v238, v238
	v_rcp_f32_e32 v239, v239
	v_lshlrev_b32_e32 v232, 16, v174
	v_and_b32_e32 v233, 0xffff0000, v174
	v_lshlrev_b32_e32 v234, 16, v175
	v_and_b32_e32 v235, 0xffff0000, v175
	v_pk_fma_f32 v[32:33], v[236:237], v[232:233], v[164:165]
	v_pk_fma_f32 v[34:35], v[238:239], v[234:235], v[166:167]
	v_pk_mul_f32 v[236:237], v[32:33], v[32:33]
	v_pk_mul_f32 v[238:239], v[34:35], v[34:35]
	v_add_f32_e32 v229, v229, v236
	v_add_f32_e32 v229, v229, v237
	v_add_f32_e32 v229, v229, v238
	v_add_f32_e32 v229, v229, v239
	v_xor_b32_e32 v232, 64, v224
	ds_bpermute_b32 v233, v232, v229
	s_waitcnt lgkmcnt(0)
	v_add_f32_e32 v229, v229, v233
	v_xor_b32_e32 v232, 0x80, v224
	ds_bpermute_b32 v233, v232, v229
	s_waitcnt lgkmcnt(0)
	v_add_f32_e32 v229, v229, v233
	s_and_saveexec_b64 s[100:101], s[98:99]
	global_atomic_add_f32 v226, v229, s[16:17] offset:576
	s_mov_b64 exec, s[100:101]
	s_waitcnt vmcnt(9)
; __device__ __forceinline__ float bf_lo(unsigned w) { return __uint_as_float(w << 16); }
; __device__ __forceinline__ float bf_hi(unsigned w) { return __uint_as_float(w & 0xffff0000u); }
; __device__ __forceinline__ float sigmoidf_(float x) { return __builtin_amdgcn_rcpf(1.0f + __expf(-x)); }
; __device__ __forceinline__ float rinv_of(float ssq) { return rsqrtf(ssq * (1.0f / 1024.0f) + EPS); }
; __device__ __forceinline__ u32x4 pack8(const f32x4 a, const f32x4 b) { u32x4 w; w.x = cvt_pk_bf16(a[0], a[1]); w.y = cvt_pk_bf16(a[2], a[3]); w.z = cvt_pk_bf16(b[0], b[1]); w.w = cvt_pk_bf16(b[2], b[3]); return w; }
;     __device__ __forceinline__ void operator()(const AccT& acc, const pg8::Unit& u, int wr, int wc, int fr, int fq) const {
;     ...
;                 for (int mm = 0; mm < 2; ++mm) { const int r = EPI_ROW(u, ai, 2 * mp + mm); rs[mm] = ssq_in[r];
; #pragma unroll
;                     for (int bj = 0; bj < 2; ++bj) { const int c = EPI_COL(u, bj); const float* hp = h + (size_t)r * D + c; hv[mm][bj][0] = *(const f32x4*)hp; hv[mm][bj][1] = *(const f32x4*)(hp + 4); pw[mm][bj] = *(const u32x4*)(pp + (size_t)r * D + c); } }
; #pragma unroll
;                 for (int mm = 0; mm < 2; ++mm) { const int m = 2 * mp + mm, r = EPI_ROW(u, ai, m); float s = 0.f; const float ri = rinv_of(rs[mm]);
; #pragma unroll
;                     for (int bj = 0; bj < 2; ++bj) { const int c = EPI_COL(u, bj); float* hp = h + (size_t)r * D + c; const u32x4 p4 = pw[mm][bj];
;                         const f32x4 a0 = acc[ai][bj][m][0] * ri, a1 = acc[ai][bj][m][1] * ri; f32x4 v0 = hv[mm][bj][0], v1 = hv[mm][bj][1];
;                         v0[0] += mul * sigmoidf_(a0[0]) * bf_lo(p4.x); v0[1] += mul * sigmoidf_(a0[1]) * bf_hi(p4.x); v0[2] += mul * sigmoidf_(a0[2]) * bf_lo(p4.y); v0[3] += mul * sigmoidf_(a0[3]) * bf_hi(p4.y);
;                         v1[0] += mul * sigmoidf_(a1[0]) * bf_lo(p4.z); v1[1] += mul * sigmoidf_(a1[1]) * bf_hi(p4.z); v1[2] += mul * sigmoidf_(a1[2]) * bf_lo(p4.w); v1[3] += mul * sigmoidf_(a1[3]) * bf_hi(p4.w);
;                         *(f32x4*)hp = v0; *(f32x4*)(hp + 4) = v1;
;                         if (hb) *(u32x4*)(hb + (size_t)r * D + c) = pack8(v0, v1);
;                         s += sq8(v0, v1); }
;                     ssq_commit(s, ssq, r, fq); }
	v_fmamk_f32 v230, v227, 0x3a800000, v225
	v_rsq_f32_e32 v230, v230
	v_mov_b32_e32 v229, 0
	v_pk_mul_f32 v[236:237], v[28:29], v[230:231] op_sel_hi:[1,0]
	v_pk_mul_f32 v[238:239], v[30:31], v[230:231] op_sel_hi:[1,0]
	v_mul_f32_e32 v236, 0xbfb8aa3b, v236
	v_mul_f32_e32 v237, 0xbfb8aa3b, v237
	v_mul_f32_e32 v238, 0xbfb8aa3b, v238
	v_mul_f32_e32 v239, 0xbfb8aa3b, v239
	v_exp_f32_e32 v236, v236
	v_exp_f32_e32 v237, v237
	v_exp_f32_e32 v238, v238
	v_exp_f32_e32 v239, v239
	v_add_f32_e32 v236, 1.0, v236
	v_add_f32_e32 v237, 1.0, v237
	v_add_f32_e32 v238, 1.0, v238
	v_add_f32_e32 v239, 1.0, v239
	v_rcp_f32_e32 v236, v236
	v_rcp_f32_e32 v237, v237
	v_rcp_f32_e32 v238, v238
	v_rcp_f32_e32 v239, v239
	v_lshlrev_b32_e32 v232, 16, v212
	v_and_b32_e32 v233, 0xffff0000, v212
	v_lshlrev_b32_e32 v234, 16, v213
	v_and_b32_e32 v235, 0xffff0000, v213
	v_pk_fma_f32 v[28:29], v[236:237], v[232:233], v[178:179]
	v_pk_fma_f32 v[30:31], v[238:239], v[234:235], v[180:181]
	v_pk_mul_f32 v[236:237], v[28:29], v[28:29]
	v_pk_mul_f32 v[238:239], v[30:31], v[30:31]
	v_add_f32_e32 v229, v229, v236
	v_add_f32_e32 v229, v229, v237
	v_add_f32_e32 v229, v229, v238
	v_add_f32_e32 v229, v229, v239
	v_pk_mul_f32 v[236:237], v[24:25], v[230:231] op_sel_hi:[1,0]
	v_pk_mul_f32 v[238:239], v[26:27], v[230:231] op_sel_hi:[1,0]
	v_mul_f32_e32 v236, 0xbfb8aa3b, v236
	v_mul_f32_e32 v237, 0xbfb8aa3b, v237
	v_mul_f32_e32 v238, 0xbfb8aa3b, v238
	v_mul_f32_e32 v239, 0xbfb8aa3b, v239
	v_exp_f32_e32 v236, v236
	v_exp_f32_e32 v237, v237
	v_exp_f32_e32 v238, v238
	v_exp_f32_e32 v239, v239
	v_add_f32_e32 v236, 1.0, v236
	v_add_f32_e32 v237, 1.0, v237
	v_add_f32_e32 v238, 1.0, v238
	v_add_f32_e32 v239, 1.0, v239
	v_rcp_f32_e32 v236, v236
	v_rcp_f32_e32 v237, v237
	v_rcp_f32_e32 v238, v238
	v_rcp_f32_e32 v239, v239
	v_lshlrev_b32_e32 v232, 16, v214
	v_and_b32_e32 v233, 0xffff0000, v214
	v_lshlrev_b32_e32 v234, 16, v215
	v_and_b32_e32 v235, 0xffff0000, v215
	v_pk_fma_f32 v[24:25], v[236:237], v[232:233], v[182:183]
	v_pk_fma_f32 v[26:27], v[238:239], v[234:235], v[184:185]
	v_pk_mul_f32 v[236:237], v[24:25], v[24:25]
	v_pk_mul_f32 v[238:239], v[26:27], v[26:27]
	v_add_f32_e32 v229, v229, v236
	v_add_f32_e32 v229, v229, v237
	v_add_f32_e32 v229, v229, v238
	v_add_f32_e32 v229, v229, v239
	v_pk_mul_f32 v[236:237], v[20:21], v[230:231] op_sel_hi:[1,0]
	v_pk_mul_f32 v[238:239], v[22:23], v[230:231] op_sel_hi:[1,0]
	v_mul_f32_e32 v236, 0xbfb8aa3b, v236
	v_mul_f32_e32 v237, 0xbfb8aa3b, v237
	v_mul_f32_e32 v238, 0xbfb8aa3b, v238
	v_mul_f32_e32 v239, 0xbfb8aa3b, v239
	v_exp_f32_e32 v236, v236
	v_exp_f32_e32 v237, v237
	v_exp_f32_e32 v238, v238
	v_exp_f32_e32 v239, v239
	v_add_f32_e32 v236, 1.0, v236
	v_add_f32_e32 v237, 1.0, v237
	v_add_f32_e32 v238, 1.0, v238
	v_add_f32_e32 v239, 1.0, v239
	v_rcp_f32_e32 v236, v236
	v_rcp_f32_e32 v237, v237
	v_rcp_f32_e32 v238, v238
	v_rcp_f32_e32 v239, v239
	v_lshlrev_b32_e32 v232, 16, v216
	v_and_b32_e32 v233, 0xffff0000, v216
	v_lshlrev_b32_e32 v234, 16, v217
	v_and_b32_e32 v235, 0xffff0000, v217
	v_pk_fma_f32 v[20:21], v[236:237], v[232:233], v[186:187]
	v_pk_fma_f32 v[22:23], v[238:239], v[234:235], v[188:189]
	v_pk_mul_f32 v[236:237], v[20:21], v[20:21]
	v_pk_mul_f32 v[238:239], v[22:23], v[22:23]
	v_add_f32_e32 v229, v229, v236
	v_add_f32_e32 v229, v229, v237
	v_add_f32_e32 v229, v229, v238
	v_add_f32_e32 v229, v229, v239
	v_pk_mul_f32 v[236:237], v[16:17], v[230:231] op_sel_hi:[1,0]
	v_pk_mul_f32 v[238:239], v[18:19], v[230:231] op_sel_hi:[1,0]
	v_mul_f32_e32 v236, 0xbfb8aa3b, v236
	v_mul_f32_e32 v237, 0xbfb8aa3b, v237
	v_mul_f32_e32 v238, 0xbfb8aa3b, v238
	v_mul_f32_e32 v239, 0xbfb8aa3b, v239
	v_exp_f32_e32 v236, v236
	v_exp_f32_e32 v237, v237
	v_exp_f32_e32 v238, v238
	v_exp_f32_e32 v239, v239
	v_add_f32_e32 v236, 1.0, v236
	v_add_f32_e32 v237, 1.0, v237
	v_add_f32_e32 v238, 1.0, v238
	v_add_f32_e32 v239, 1.0, v239
	v_rcp_f32_e32 v236, v236
	v_rcp_f32_e32 v237, v237
	v_rcp_f32_e32 v238, v238
	v_rcp_f32_e32 v239, v239
	v_lshlrev_b32_e32 v232, 16, v218
	v_and_b32_e32 v233, 0xffff0000, v218
	v_lshlrev_b32_e32 v234, 16, v219
	v_and_b32_e32 v235, 0xffff0000, v219
	v_pk_fma_f32 v[16:17], v[236:237], v[232:233], v[190:191]
	v_pk_fma_f32 v[18:19], v[238:239], v[234:235], v[192:193]
	v_pk_mul_f32 v[236:237], v[16:17], v[16:17]
	v_pk_mul_f32 v[238:239], v[18:19], v[18:19]
	v_add_f32_e32 v229, v229, v236
	v_add_f32_e32 v229, v229, v237
	v_add_f32_e32 v229, v229, v238
	v_add_f32_e32 v229, v229, v239
	v_xor_b32_e32 v232, 64, v224
	ds_bpermute_b32 v233, v232, v229
	s_waitcnt lgkmcnt(0)
	v_add_f32_e32 v229, v229, v233
	v_xor_b32_e32 v232, 0x80, v224
	ds_bpermute_b32 v233, v232, v229
	s_waitcnt lgkmcnt(0)
	v_add_f32_e32 v229, v229, v233
	s_and_saveexec_b64 s[100:101], s[98:99]
	global_atomic_add_f32 v226, v229, s[16:17] offset:640
	s_mov_b64 exec, s[100:101]
	s_waitcnt vmcnt(3)
; __device__ __forceinline__ float bf_lo(unsigned w) { return __uint_as_float(w << 16); }
; __device__ __forceinline__ float bf_hi(unsigned w) { return __uint_as_float(w & 0xffff0000u); }
; __device__ __forceinline__ float sigmoidf_(float x) { return __builtin_amdgcn_rcpf(1.0f + __expf(-x)); }
; __device__ __forceinline__ float rinv_of(float ssq) { return rsqrtf(ssq * (1.0f / 1024.0f) + EPS); }
; __device__ __forceinline__ u32x4 pack8(const f32x4 a, const f32x4 b) { u32x4 w; w.x = cvt_pk_bf16(a[0], a[1]); w.y = cvt_pk_bf16(a[2], a[3]); w.z = cvt_pk_bf16(b[0], b[1]); w.w = cvt_pk_bf16(b[2], b[3]); return w; }
;     __device__ __forceinline__ void operator()(const AccT& acc, const pg8::Unit& u, int wr, int wc, int fr, int fq) const {
;     ...
;                 for (int mm = 0; mm < 2; ++mm) { const int r = EPI_ROW(u, ai, 2 * mp + mm); rs[mm] = ssq_in[r];
; #pragma unroll
;                     for (int bj = 0; bj < 2; ++bj) { const int c = EPI_COL(u, bj); const float* hp = h + (size_t)r * D + c; hv[mm][bj][0] = *(const f32x4*)hp; hv[mm][bj][1] = *(const f32x4*)(hp + 4); pw[mm][bj] = *(const u32x4*)(pp + (size_t)r * D + c); } }
; #pragma unroll
;                 for (int mm = 0; mm < 2; ++mm) { const int m = 2 * mp + mm, r = EPI_ROW(u, ai, m); float s = 0.f; const float ri = rinv_of(rs[mm]);
; #pragma unroll
;                     for (int bj = 0; bj < 2; ++bj) { const int c = EPI_COL(u, bj); float* hp = h + (size_t)r * D + c; const u32x4 p4 = pw[mm][bj];
;                         const f32x4 a0 = acc[ai][bj][m][0] * ri, a1 = acc[ai][bj][m][1] * ri; f32x4 v0 = hv[mm][bj][0], v1 = hv[mm][bj][1];
;                         v0[0] += mul * sigmoidf_(a0[0]) * bf_lo(p4.x); v0[1] += mul * sigmoidf_(a0[1]) * bf_hi(p4.x); v0[2] += mul * sigmoidf_(a0[2]) * bf_lo(p4.y); v0[3] += mul * sigmoidf_(a0[3]) * bf_hi(p4.y);
;                         v1[0] += mul * sigmoidf_(a1[0]) * bf_lo(p4.z); v1[1] += mul * sigmoidf_(a1[1]) * bf_hi(p4.z); v1[2] += mul * sigmoidf_(a1[2]) * bf_lo(p4.w); v1[3] += mul * sigmoidf_(a1[3]) * bf_hi(p4.w);
;                         *(f32x4*)hp = v0; *(f32x4*)(hp + 4) = v1;
;                         if (hb) *(u32x4*)(hb + (size_t)r * D + c) = pack8(v0, v1);
;                         s += sq8(v0, v1); }
;                     ssq_commit(s, ssq, r, fq); }
;                 asm volatile("" ::: "memory"); }
;     }
	v_fmamk_f32 v230, v228, 0x3a800000, v225
	v_rsq_f32_e32 v230, v230
	v_mov_b32_e32 v229, 0
	v_pk_mul_f32 v[236:237], v[12:13], v[230:231] op_sel_hi:[1,0]
	v_pk_mul_f32 v[238:239], v[14:15], v[230:231] op_sel_hi:[1,0]
	v_mul_f32_e32 v236, 0xbfb8aa3b, v236
	v_mul_f32_e32 v237, 0xbfb8aa3b, v237
	v_mul_f32_e32 v238, 0xbfb8aa3b, v238
	v_mul_f32_e32 v239, 0xbfb8aa3b, v239
	v_exp_f32_e32 v236, v236
	v_exp_f32_e32 v237, v237
	v_exp_f32_e32 v238, v238
	v_exp_f32_e32 v239, v239
	v_add_f32_e32 v236, 1.0, v236
	v_add_f32_e32 v237, 1.0, v237
	v_add_f32_e32 v238, 1.0, v238
	v_add_f32_e32 v239, 1.0, v239
	v_rcp_f32_e32 v236, v236
	v_rcp_f32_e32 v237, v237
	v_rcp_f32_e32 v238, v238
	v_rcp_f32_e32 v239, v239
	v_lshlrev_b32_e32 v232, 16, v220
	v_and_b32_e32 v233, 0xffff0000, v220
	v_lshlrev_b32_e32 v234, 16, v221
	v_and_b32_e32 v235, 0xffff0000, v221
	v_pk_fma_f32 v[12:13], v[236:237], v[232:233], v[194:195]
	v_pk_fma_f32 v[14:15], v[238:239], v[234:235], v[196:197]
	v_pk_mul_f32 v[236:237], v[12:13], v[12:13]
	v_pk_mul_f32 v[238:239], v[14:15], v[14:15]
	v_add_f32_e32 v229, v229, v236
	v_add_f32_e32 v229, v229, v237
	v_add_f32_e32 v229, v229, v238
	v_add_f32_e32 v229, v229, v239
	v_pk_mul_f32 v[236:237], v[8:9], v[230:231] op_sel_hi:[1,0]
	v_pk_mul_f32 v[238:239], v[10:11], v[230:231] op_sel_hi:[1,0]
	v_mul_f32_e32 v236, 0xbfb8aa3b, v236
	v_mul_f32_e32 v237, 0xbfb8aa3b, v237
	v_mul_f32_e32 v238, 0xbfb8aa3b, v238
	v_mul_f32_e32 v239, 0xbfb8aa3b, v239
	v_exp_f32_e32 v236, v236
	v_exp_f32_e32 v237, v237
	v_exp_f32_e32 v238, v238
	v_exp_f32_e32 v239, v239
	v_add_f32_e32 v236, 1.0, v236
	v_add_f32_e32 v237, 1.0, v237
	v_add_f32_e32 v238, 1.0, v238
	v_add_f32_e32 v239, 1.0, v239
	v_rcp_f32_e32 v236, v236
	v_rcp_f32_e32 v237, v237
	v_rcp_f32_e32 v238, v238
	v_rcp_f32_e32 v239, v239
	v_lshlrev_b32_e32 v232, 16, v222
	v_and_b32_e32 v233, 0xffff0000, v222
	v_lshlrev_b32_e32 v234, 16, v223
	v_and_b32_e32 v235, 0xffff0000, v223
	v_pk_fma_f32 v[8:9], v[236:237], v[232:233], v[198:199]
	v_pk_fma_f32 v[10:11], v[238:239], v[234:235], v[200:201]
	v_pk_mul_f32 v[236:237], v[8:9], v[8:9]
	v_pk_mul_f32 v[238:239], v[10:11], v[10:11]
	v_add_f32_e32 v229, v229, v236
	v_add_f32_e32 v229, v229, v237
	v_add_f32_e32 v229, v229, v238
	v_add_f32_e32 v229, v229, v239
	v_pk_mul_f32 v[236:237], v[4:5], v[230:231] op_sel_hi:[1,0]
	v_pk_mul_f32 v[238:239], v[6:7], v[230:231] op_sel_hi:[1,0]
	v_mul_f32_e32 v236, 0xbfb8aa3b, v236
	v_mul_f32_e32 v237, 0xbfb8aa3b, v237
	v_mul_f32_e32 v238, 0xbfb8aa3b, v238
	v_mul_f32_e32 v239, 0xbfb8aa3b, v239
	v_exp_f32_e32 v236, v236
	v_exp_f32_e32 v237, v237
	v_exp_f32_e32 v238, v238
	v_exp_f32_e32 v239, v239
	v_add_f32_e32 v236, 1.0, v236
	v_add_f32_e32 v237, 1.0, v237
	v_add_f32_e32 v238, 1.0, v238
	v_add_f32_e32 v239, 1.0, v239
	v_rcp_f32_e32 v236, v236
	v_rcp_f32_e32 v237, v237
	v_rcp_f32_e32 v238, v238
	v_rcp_f32_e32 v239, v239
	v_lshlrev_b32_e32 v232, 16, v244
	v_and_b32_e32 v233, 0xffff0000, v244
	v_lshlrev_b32_e32 v234, 16, v245
	v_and_b32_e32 v235, 0xffff0000, v245
	v_pk_fma_f32 v[4:5], v[236:237], v[232:233], v[202:203]
	v_pk_fma_f32 v[6:7], v[238:239], v[234:235], v[204:205]
	v_pk_mul_f32 v[236:237], v[4:5], v[4:5]
	v_pk_mul_f32 v[238:239], v[6:7], v[6:7]
	v_add_f32_e32 v229, v229, v236
	v_add_f32_e32 v229, v229, v237
	v_add_f32_e32 v229, v229, v238
	v_add_f32_e32 v229, v229, v239
	v_pk_mul_f32 v[236:237], v[0:1], v[230:231] op_sel_hi:[1,0]
	v_pk_mul_f32 v[238:239], v[2:3], v[230:231] op_sel_hi:[1,0]
	v_mul_f32_e32 v236, 0xbfb8aa3b, v236
	v_mul_f32_e32 v237, 0xbfb8aa3b, v237
	v_mul_f32_e32 v238, 0xbfb8aa3b, v238
	v_mul_f32_e32 v239, 0xbfb8aa3b, v239
	v_exp_f32_e32 v236, v236
	v_exp_f32_e32 v237, v237
	v_exp_f32_e32 v238, v238
	v_exp_f32_e32 v239, v239
	v_add_f32_e32 v236, 1.0, v236
	v_add_f32_e32 v237, 1.0, v237
	v_add_f32_e32 v238, 1.0, v238
	v_add_f32_e32 v239, 1.0, v239
	v_rcp_f32_e32 v236, v236
	v_rcp_f32_e32 v237, v237
	v_rcp_f32_e32 v238, v238
	v_rcp_f32_e32 v239, v239
	v_lshlrev_b32_e32 v232, 16, v246
	v_and_b32_e32 v233, 0xffff0000, v246
	v_lshlrev_b32_e32 v234, 16, v247
	v_and_b32_e32 v235, 0xffff0000, v247
	v_pk_fma_f32 v[0:1], v[236:237], v[232:233], v[206:207]
	v_pk_fma_f32 v[2:3], v[238:239], v[234:235], v[208:209]
	v_pk_mul_f32 v[236:237], v[0:1], v[0:1]
	v_pk_mul_f32 v[238:239], v[2:3], v[2:3]
	v_add_f32_e32 v229, v229, v236
	v_add_f32_e32 v229, v229, v237
	v_add_f32_e32 v229, v229, v238
	v_add_f32_e32 v229, v229, v239
	v_xor_b32_e32 v232, 64, v224
	ds_bpermute_b32 v233, v232, v229
	s_waitcnt lgkmcnt(0)
	v_add_f32_e32 v229, v229, v233
	v_xor_b32_e32 v232, 0x80, v224
	ds_bpermute_b32 v233, v232, v229
	s_waitcnt lgkmcnt(0)
	v_add_f32_e32 v229, v229, v233
	s_and_saveexec_b64 s[100:101], s[98:99]
	global_atomic_add_f32 v226, v229, s[16:17] offset:704
	s_mov_b64 exec, s[100:101]
	s_mov_b64 s[12:13], exec
	s_branch .LBB0_2611

; __device__ __forceinline__ void fused_final_tile(const Params& P, int pm, int pn, unsigned* cnt, unsigned char* lds_f) {
;     const int tid = threadIdx.x;
;     asm volatile("s_waitcnt vmcnt(0)" ::: "memory");
;     __syncthreads();
;     if (tid == 0) {
;         __hip_atomic_fetch_add(cnt + 16 * pm, 1u, __ATOMIC_RELAXED, __HIP_MEMORY_SCOPE_AGENT);
;         unsigned sp = 0;
;         while (__hip_atomic_load(cnt + 16 * pm, __ATOMIC_RELAXED, __HIP_MEMORY_SCOPE_AGENT) < 4u) { __builtin_amdgcn_s_sleep(2); if (++sp > (1u << 22)) break; }
.LBB0_2645:
	s_add_i32 s3, s10, s8
	s_ashr_i32 s8, s3, 31
	s_lshr_b32 s8, s8, 28
	s_add_i32 s8, s3, s8
	s_ashr_i32 s9, s8, 4
	s_and_b32 s8, s8, 0xfff0
	s_sub_i32 s8, s3, s8
	s_bfe_i32 s3, s8, 0x80000
	s_bfe_u32 s3, s3, 0x2000d
	s_add_i32 s3, s8, s3
	s_lshl_b32 s22, s9, 2
	s_and_b32 s9, s3, 0xfc
	s_sub_i32 s8, s8, s9
	s_waitcnt vmcnt(0)
	s_sext_i32_i8 s8, s8
	s_add_i32 s22, s22, s8
	s_waitcnt lgkmcnt(0)
	s_barrier
	s_and_saveexec_b64 s[8:9], s[4:5]
	s_cbranch_execz .LBB0_2656
	s_lshl_b32 s10, s22, 4
	s_ashr_i32 s11, s10, 31
	s_lshl_b64 s[10:11], s[10:11], 2
	s_mov_b64 s[12:13], exec
	s_add_u32 s10, s54, s10
	s_addc_u32 s11, s55, s11
	v_mbcnt_lo_u32_b32 v190, s12, 0
	s_add_u32 s10, s10, 0x3089c00
	v_mbcnt_hi_u32_b32 v190, s13, v190
	s_addc_u32 s11, s11, 0
	v_cmp_eq_u32_e32 vcc, 0, v190
	s_and_saveexec_b64 s[20:21], vcc
	s_cbranch_execz .LBB0_2648
	s_bcnt1_i32_b64 s12, s[12:13]
	v_mov_b32_e32 v190, 0
	v_mov_b32_e32 v191, s12
	global_atomic_add v190, v191, s[10:11]
.LBB0_2648:
	s_or_b64 exec, exec, s[20:21]
	s_mov_b32 s20, 0x400001
	v_mov_b32_e32 v190, 0
	s_branch .LBB0_2650

; __device__ __forceinline__ float rinv_of(float ssq) { return rsqrtf(ssq * (1.0f / 1024.0f) + EPS); }
; __device__ __forceinline__ void fused_final_tile(const Params& P, int pm, int pn, unsigned* cnt, unsigned char* lds_f) {
;     ...
;         while (__hip_atomic_load(cnt + 16 * pm, __ATOMIC_RELAXED, __HIP_MEMORY_SCOPE_AGENT) < 4u) { __builtin_amdgcn_s_sleep(2); if (++sp > (1u << 22)) break; }
;     }
;     __syncthreads();
;     float* h = P.out + OUT_Y; float* ssq = (float*)(P.ws + O_SSQ) + 5 * M; const float* nf = P.in[9];
;     float* rs = (float*)lds_f;
;     if (tid < 256) rs[tid] = rinv_of(__hip_atomic_load(ssq + pm * 256 + tid, __ATOMIC_RELAXED, __HIP_MEMORY_SCOPE_AGENT));
;     __syncthreads();
;     const int c4 = (tid & 63) * 4; const f32x4 g = *(const f32x4*)(nf + pn * 256 + c4);
;     for (int i0 = 0; i0 < 32; i0 += 8) {
;         f32x4 v[8];
; #pragma unroll
;         for (int j = 0; j < 8; ++j) { const int row = (i0 + j) * 8 + (tid >> 6); v[j] = *(const f32x4*)(h + (size_t)(pm * 256 + row) * D + pn * 256 + c4); }
; #pragma unroll
;         for (int j = 0; j < 8; ++j) { const int row = (i0 + j) * 8 + (tid >> 6); *(f32x4*)(h + (size_t)(pm * 256 + row) * D + pn * 256 + c4) = v[j] * rs[row] * g; } }
.LBB0_2650:
	global_load_dword v191, v190, s[10:11] sc1
	s_mov_b64 s[12:13], -1
	s_waitcnt vmcnt(0)
	v_cmp_lt_u32_e32 vcc, 3, v191
	s_cbranch_vccnz .LBB0_2649
	s_sleep 2
	global_load_dword v191, v190, s[10:11] sc1
	s_waitcnt vmcnt(0)
	v_cmp_gt_u32_e32 vcc, 4, v191
	s_cbranch_vccz .LBB0_2649
	s_sleep 2
	global_load_dword v191, v190, s[10:11] sc1
	s_waitcnt vmcnt(0)
	v_cmp_gt_u32_e32 vcc, 4, v191
	s_cbranch_vccz .LBB0_2649
	s_sleep 2
	global_load_dword v191, v190, s[10:11] sc1
	s_waitcnt vmcnt(0)
	v_cmp_gt_u32_e32 vcc, 4, v191
	s_cbranch_vccz .LBB0_2649
	s_sleep 2
	global_load_dword v191, v190, s[10:11] sc1
	s_waitcnt vmcnt(0)
	v_cmp_gt_u32_e32 vcc, 4, v191
	s_cbranch_vccz .LBB0_2649
	s_add_i32 s20, s20, -5
	s_cmp_eq_u32 s20, 0
	s_cselect_b64 s[12:13], -1, 0
	s_sleep 2
	s_branch .LBB0_2649
.LBB0_2656:
	s_or_b64 exec, exec, s[8:9]
	s_load_dwordx2 s[8:9], s[0:1], 0xb8
	s_load_dwordx2 s[10:11], s[0:1], 0x48
	s_movk_i32 s12, 0xff
	v_cmp_lt_u32_e32 vcc, s12, v210
	s_barrier
	s_waitcnt lgkmcnt(0)
	s_and_saveexec_b64 s[12:13], vcc
	s_xor_b64 s[12:13], exec, s[12:13]
	s_lshl_b32 s20, s22, 8
	s_or_saveexec_b64 s[12:13], s[12:13]
	v_mov_b32_e32 v200, s20
	s_xor_b64 exec, exec, s[12:13]
	s_cbranch_execz .LBB0_2660
	s_load_dwordx2 s[20:21], s[0:1], 0xc0
	s_lshl_b32 s22, s22, 8
	s_ashr_i32 s23, s22, 31
	s_lshl_b64 s[24:25], s[22:23], 2
	v_lshlrev_b32_e32 v190, 2, v210
	s_waitcnt lgkmcnt(0)
	s_add_u32 s20, s20, s24
	s_addc_u32 s21, s21, s25
	v_mov_b32_e32 v191, 0
	v_lshl_add_u64 v[192:193], s[20:21], 0, v[190:191]
	v_add_co_u32_e32 v192, vcc, 0x2fdd000, v192
	s_mov_b32 s20, 0x800000
	s_nop 0
	v_addc_co_u32_e32 v193, vcc, 0, v193, vcc
	global_load_dword v191, v[192:193], off offset:1024 sc1
	v_mov_b32_e32 v192, 0x358637bd
	v_add_u32_e32 v190, 0, v190
	v_mov_b32_e32 v200, s22
	s_waitcnt vmcnt(0)
	v_fmac_f32_e32 v192, 0x3a800000, v191
	v_mul_f32_e32 v191, 0x4b800000, v192
	v_cmp_gt_f32_e32 vcc, s20, v192
	s_nop 1
	v_cndmask_b32_e32 v191, v192, v191, vcc
	v_rsq_f32_e32 v191, v191
	s_nop 0
	v_mul_f32_e32 v192, 0x45800000, v191
	v_cndmask_b32_e32 v191, v191, v192, vcc
	ds_write_b32 v190, v191
.LBB0_2660:
	s_or_b64 exec, exec, s[12:13]
	s_sext_i32_i8 s3, s3
	s_lshl_b32 s3, s3, 6
	s_and_b32 s12, s3, 0xffffff00
	s_ashr_i32 s13, s12, 31
	s_lshl_b64 s[12:13], s[12:13], 2
	s_add_u32 s10, s10, s12
	s_addc_u32 s11, s11, s13
	v_lshrrev_b32_e32 v201, 6, v210
	v_lshlrev_b32_e32 v190, 4, v210
	v_or_b32_e32 v198, v200, v201
	s_add_u32 s8, s8, s12
	v_and_b32_e32 v194, 0x3f0, v190
	v_mov_b32_e32 v195, 0
	s_addc_u32 s9, s9, s13
	v_ashrrev_i32_e32 v199, 31, v198
	s_waitcnt lgkmcnt(0)
	s_barrier
	s_load_dwordx2 s[100:101], s[0:1], 0x48
	v_and_b32_e32 v226, 0xff, v241
	v_lshlrev_b32_e32 v226, 2, v226
	ds_read_b32 v128, v226
	ds_read_b32 v130, v226 offset:64
	ds_read_b32 v132, v226 offset:128
	ds_read_b32 v134, v226 offset:192
	ds_read_b32 v136, v226 offset:512
	ds_read_b32 v138, v226 offset:576
	ds_read_b32 v140, v226 offset:640
	ds_read_b32 v142, v226 offset:704
	v_lshlrev_b32_e32 v227, 2, v242
	s_waitcnt lgkmcnt(0)
	global_load_dwordx4 v[160:163], v227, s[100:101]
	global_load_dwordx4 v[164:167], v227, s[100:101] offset:16
	global_load_dwordx4 v[168:171], v227, s[100:101] offset:512
	global_load_dwordx4 v[172:175], v227, s[100:101] offset:528
	s_waitcnt vmcnt(0)
	v_mov_b32_e32 v176, v243
	v_pk_mul_f32 v[124:125], v[124:125], v[128:129] op_sel_hi:[1,0]
	v_pk_mul_f32 v[126:127], v[126:127], v[128:129] op_sel_hi:[1,0]
	v_pk_mul_f32 v[124:125], v[124:125], v[160:161]
	v_pk_mul_f32 v[126:127], v[126:127], v[162:163]
	global_store_dwordx4 v176, v[124:127], s[52:53]
	v_pk_mul_f32 v[120:121], v[120:121], v[128:129] op_sel_hi:[1,0]
	v_pk_mul_f32 v[122:123], v[122:123], v[128:129] op_sel_hi:[1,0]
	v_pk_mul_f32 v[120:121], v[120:121], v[164:165]
	v_pk_mul_f32 v[122:123], v[122:123], v[166:167]
	global_store_dwordx4 v176, v[120:123], s[52:53] offset:16
	v_pk_mul_f32 v[116:117], v[116:117], v[128:129] op_sel_hi:[1,0]
	v_pk_mul_f32 v[118:119], v[118:119], v[128:129] op_sel_hi:[1,0]
	v_pk_mul_f32 v[116:117], v[116:117], v[168:169]
	v_pk_mul_f32 v[118:119], v[118:119], v[170:171]
	global_store_dwordx4 v176, v[116:119], s[52:53] offset:512
	v_pk_mul_f32 v[112:113], v[112:113], v[128:129] op_sel_hi:[1,0]
	v_pk_mul_f32 v[114:115], v[114:115], v[128:129] op_sel_hi:[1,0]
	v_pk_mul_f32 v[112:113], v[112:113], v[172:173]
	v_pk_mul_f32 v[114:115], v[114:115], v[174:175]
	global_store_dwordx4 v176, v[112:115], s[52:53] offset:528
	v_add_u32_e32 v176, 0x10000, v243
	v_pk_mul_f32 v[108:109], v[108:109], v[130:131] op_sel_hi:[1,0]
	v_pk_mul_f32 v[110:111], v[110:111], v[130:131] op_sel_hi:[1,0]
	v_pk_mul_f32 v[108:109], v[108:109], v[160:161]
	v_pk_mul_f32 v[110:111], v[110:111], v[162:163]
	global_store_dwordx4 v176, v[108:111], s[52:53]
	v_pk_mul_f32 v[104:105], v[104:105], v[130:131] op_sel_hi:[1,0]
	v_pk_mul_f32 v[106:107], v[106:107], v[130:131] op_sel_hi:[1,0]
	v_pk_mul_f32 v[104:105], v[104:105], v[164:165]
	v_pk_mul_f32 v[106:107], v[106:107], v[166:167]
	global_store_dwordx4 v176, v[104:107], s[52:53] offset:16
	v_pk_mul_f32 v[100:101], v[100:101], v[130:131] op_sel_hi:[1,0]
	v_pk_mul_f32 v[102:103], v[102:103], v[130:131] op_sel_hi:[1,0]
	v_pk_mul_f32 v[100:101], v[100:101], v[168:169]
	v_pk_mul_f32 v[102:103], v[102:103], v[170:171]
	global_store_dwordx4 v176, v[100:103], s[52:53] offset:512
	v_pk_mul_f32 v[96:97], v[96:97], v[130:131] op_sel_hi:[1,0]
	v_pk_mul_f32 v[98:99], v[98:99], v[130:131] op_sel_hi:[1,0]
	v_pk_mul_f32 v[96:97], v[96:97], v[172:173]
	v_pk_mul_f32 v[98:99], v[98:99], v[174:175]
	global_store_dwordx4 v176, v[96:99], s[52:53] offset:528
	v_add_u32_e32 v176, 0x20000, v243
; __device__ __forceinline__ float bf_lo(unsigned w) { return __uint_as_float(w << 16); }
; __device__ __forceinline__ float bf_hi(unsigned w) { return __uint_as_float(w & 0xffff0000u); }
; __device__ __forceinline__ float sigmoidf_(float x) { return __builtin_amdgcn_rcpf(1.0f + __expf(-x)); }
; __device__ __forceinline__ u32x4 pack8(const f32x4 a, const f32x4 b) { u32x4 w; w.x = cvt_pk_bf16(a[0], a[1]); w.y = cvt_pk_bf16(a[2], a[3]); w.z = cvt_pk_bf16(b[0], b[1]); w.w = cvt_pk_bf16(b[2], b[3]); return w; }
;     __device__ __forceinline__ void operator()(const AccT& acc, const pg8::Unit& u, int wr, int wc, int fr, int fq) const {
;     ...
;                         v0[0] += mul * sigmoidf_(a0[0]) * bf_lo(p4.x); v0[1] += mul * sigmoidf_(a0[1]) * bf_hi(p4.x); v0[2] += mul * sigmoidf_(a0[2]) * bf_lo(p4.y); v0[3] += mul * sigmoidf_(a0[3]) * bf_hi(p4.y);
;                         v1[0] += mul * sigmoidf_(a1[0]) * bf_lo(p4.z); v1[1] += mul * sigmoidf_(a1[1]) * bf_hi(p4.z); v1[2] += mul * sigmoidf_(a1[2]) * bf_lo(p4.w); v1[3] += mul * sigmoidf_(a1[3]) * bf_hi(p4.w);
;                         *(f32x4*)hp = v0; *(f32x4*)(hp + 4) = v1;
;                         if (hb) *(u32x4*)(hb + (size_t)r * D + c) = pack8(v0, v1);
; __device__ __forceinline__ void fused_final_tile(const Params& P, int pm, int pn, unsigned* cnt, unsigned char* lds_f) {
;     ...
;     const int c4 = (tid & 63) * 4; const f32x4 g = *(const f32x4*)(nf + pn * 256 + c4);
;     for (int i0 = 0; i0 < 32; i0 += 8) {
;         f32x4 v[8];
; #pragma unroll
;         for (int j = 0; j < 8; ++j) { const int row = (i0 + j) * 8 + (tid >> 6); v[j] = *(const f32x4*)(h + (size_t)(pm * 256 + row) * D + pn * 256 + c4); }
; #pragma unroll
;         for (int j = 0; j < 8; ++j) { const int row = (i0 + j) * 8 + (tid >> 6); *(f32x4*)(h + (size_t)(pm * 256 + row) * D + pn * 256 + c4) = v[j] * rs[row] * g; } }
	v_pk_mul_f32 v[92:93], v[92:93], v[132:133] op_sel_hi:[1,0]
	v_pk_mul_f32 v[94:95], v[94:95], v[132:133] op_sel_hi:[1,0]
	v_pk_mul_f32 v[92:93], v[92:93], v[160:161]
	v_pk_mul_f32 v[94:95], v[94:95], v[162:163]
	global_store_dwordx4 v176, v[92:95], s[52:53]
	v_pk_mul_f32 v[88:89], v[88:89], v[132:133] op_sel_hi:[1,0]
	v_pk_mul_f32 v[90:91], v[90:91], v[132:133] op_sel_hi:[1,0]
	v_pk_mul_f32 v[88:89], v[88:89], v[164:165]
	v_pk_mul_f32 v[90:91], v[90:91], v[166:167]
	global_store_dwordx4 v176, v[88:91], s[52:53] offset:16
	v_pk_mul_f32 v[84:85], v[84:85], v[132:133] op_sel_hi:[1,0]
	v_pk_mul_f32 v[86:87], v[86:87], v[132:133] op_sel_hi:[1,0]
	v_pk_mul_f32 v[84:85], v[84:85], v[168:169]
	v_pk_mul_f32 v[86:87], v[86:87], v[170:171]
	global_store_dwordx4 v176, v[84:87], s[52:53] offset:512
	v_pk_mul_f32 v[80:81], v[80:81], v[132:133] op_sel_hi:[1,0]
	v_pk_mul_f32 v[82:83], v[82:83], v[132:133] op_sel_hi:[1,0]
	v_pk_mul_f32 v[80:81], v[80:81], v[172:173]
	v_pk_mul_f32 v[82:83], v[82:83], v[174:175]
	global_store_dwordx4 v176, v[80:83], s[52:53] offset:528
	v_add_u32_e32 v176, 0x30000, v243
	v_pk_mul_f32 v[76:77], v[76:77], v[134:135] op_sel_hi:[1,0]
	v_pk_mul_f32 v[78:79], v[78:79], v[134:135] op_sel_hi:[1,0]
	v_pk_mul_f32 v[76:77], v[76:77], v[160:161]
	v_pk_mul_f32 v[78:79], v[78:79], v[162:163]
	global_store_dwordx4 v176, v[76:79], s[52:53]
	v_pk_mul_f32 v[72:73], v[72:73], v[134:135] op_sel_hi:[1,0]
	v_pk_mul_f32 v[74:75], v[74:75], v[134:135] op_sel_hi:[1,0]
	v_pk_mul_f32 v[72:73], v[72:73], v[164:165]
	v_pk_mul_f32 v[74:75], v[74:75], v[166:167]
	global_store_dwordx4 v176, v[72:75], s[52:53] offset:16
	v_pk_mul_f32 v[68:69], v[68:69], v[134:135] op_sel_hi:[1,0]
	v_pk_mul_f32 v[70:71], v[70:71], v[134:135] op_sel_hi:[1,0]
	v_pk_mul_f32 v[68:69], v[68:69], v[168:169]
	v_pk_mul_f32 v[70:71], v[70:71], v[170:171]
	global_store_dwordx4 v176, v[68:71], s[52:53] offset:512
	v_pk_mul_f32 v[64:65], v[64:65], v[134:135] op_sel_hi:[1,0]
	v_pk_mul_f32 v[66:67], v[66:67], v[134:135] op_sel_hi:[1,0]
	v_pk_mul_f32 v[64:65], v[64:65], v[172:173]
	v_pk_mul_f32 v[66:67], v[66:67], v[174:175]
	global_store_dwordx4 v176, v[64:67], s[52:53] offset:528
	v_add_u32_e32 v176, 0x80000, v243
	v_pk_mul_f32 v[60:61], v[60:61], v[136:137] op_sel_hi:[1,0]
	v_pk_mul_f32 v[62:63], v[62:63], v[136:137] op_sel_hi:[1,0]
	v_pk_mul_f32 v[60:61], v[60:61], v[160:161]
	v_pk_mul_f32 v[62:63], v[62:63], v[162:163]
	global_store_dwordx4 v176, v[60:63], s[52:53]
	v_pk_mul_f32 v[56:57], v[56:57], v[136:137] op_sel_hi:[1,0]
	v_pk_mul_f32 v[58:59], v[58:59], v[136:137] op_sel_hi:[1,0]
	v_pk_mul_f32 v[56:57], v[56:57], v[164:165]
	v_pk_mul_f32 v[58:59], v[58:59], v[166:167]
	global_store_dwordx4 v176, v[56:59], s[52:53] offset:16
	v_pk_mul_f32 v[52:53], v[52:53], v[136:137] op_sel_hi:[1,0]
	v_pk_mul_f32 v[54:55], v[54:55], v[136:137] op_sel_hi:[1,0]
	v_pk_mul_f32 v[52:53], v[52:53], v[168:169]
	v_pk_mul_f32 v[54:55], v[54:55], v[170:171]
	global_store_dwordx4 v176, v[52:55], s[52:53] offset:512
	v_pk_mul_f32 v[48:49], v[48:49], v[136:137] op_sel_hi:[1,0]
	v_pk_mul_f32 v[50:51], v[50:51], v[136:137] op_sel_hi:[1,0]
	v_pk_mul_f32 v[48:49], v[48:49], v[172:173]
	v_pk_mul_f32 v[50:51], v[50:51], v[174:175]
	global_store_dwordx4 v176, v[48:51], s[52:53] offset:528
	v_add_u32_e32 v176, 0x90000, v243
	v_pk_mul_f32 v[44:45], v[44:45], v[138:139] op_sel_hi:[1,0]
	v_pk_mul_f32 v[46:47], v[46:47], v[138:139] op_sel_hi:[1,0]
	v_pk_mul_f32 v[44:45], v[44:45], v[160:161]
	v_pk_mul_f32 v[46:47], v[46:47], v[162:163]
	global_store_dwordx4 v176, v[44:47], s[52:53]
	v_pk_mul_f32 v[40:41], v[40:41], v[138:139] op_sel_hi:[1,0]
	v_pk_mul_f32 v[42:43], v[42:43], v[138:139] op_sel_hi:[1,0]
	v_pk_mul_f32 v[40:41], v[40:41], v[164:165]
	v_pk_mul_f32 v[42:43], v[42:43], v[166:167]
	global_store_dwordx4 v176, v[40:43], s[52:53] offset:16
	v_pk_mul_f32 v[36:37], v[36:37], v[138:139] op_sel_hi:[1,0]
	v_pk_mul_f32 v[38:39], v[38:39], v[138:139] op_sel_hi:[1,0]
	v_pk_mul_f32 v[36:37], v[36:37], v[168:169]
	v_pk_mul_f32 v[38:39], v[38:39], v[170:171]
	global_store_dwordx4 v176, v[36:39], s[52:53] offset:512
	v_pk_mul_f32 v[32:33], v[32:33], v[138:139] op_sel_hi:[1,0]
	v_pk_mul_f32 v[34:35], v[34:35], v[138:139] op_sel_hi:[1,0]
	v_pk_mul_f32 v[32:33], v[32:33], v[172:173]
	v_pk_mul_f32 v[34:35], v[34:35], v[174:175]
	global_store_dwordx4 v176, v[32:35], s[52:53] offset:528
	v_add_u32_e32 v176, 0xa0000, v243
	v_pk_mul_f32 v[28:29], v[28:29], v[140:141] op_sel_hi:[1,0]
	v_pk_mul_f32 v[30:31], v[30:31], v[140:141] op_sel_hi:[1,0]
	v_pk_mul_f32 v[28:29], v[28:29], v[160:161]
	v_pk_mul_f32 v[30:31], v[30:31], v[162:163]
	global_store_dwordx4 v176, v[28:31], s[52:53]
	v_pk_mul_f32 v[24:25], v[24:25], v[140:141] op_sel_hi:[1,0]
	v_pk_mul_f32 v[26:27], v[26:27], v[140:141] op_sel_hi:[1,0]
	v_pk_mul_f32 v[24:25], v[24:25], v[164:165]
	v_pk_mul_f32 v[26:27], v[26:27], v[166:167]
	global_store_dwordx4 v176, v[24:27], s[52:53] offset:16
	v_pk_mul_f32 v[20:21], v[20:21], v[140:141] op_sel_hi:[1,0]
	v_pk_mul_f32 v[22:23], v[22:23], v[140:141] op_sel_hi:[1,0]
	v_pk_mul_f32 v[20:21], v[20:21], v[168:169]
	v_pk_mul_f32 v[22:23], v[22:23], v[170:171]
	global_store_dwordx4 v176, v[20:23], s[52:53] offset:512
	v_pk_mul_f32 v[16:17], v[16:17], v[140:141] op_sel_hi:[1,0]
	v_pk_mul_f32 v[18:19], v[18:19], v[140:141] op_sel_hi:[1,0]
	v_pk_mul_f32 v[16:17], v[16:17], v[172:173]
	v_pk_mul_f32 v[18:19], v[18:19], v[174:175]
	global_store_dwordx4 v176, v[16:19], s[52:53] offset:528
	v_add_u32_e32 v176, 0xb0000, v243
	v_pk_mul_f32 v[12:13], v[12:13], v[142:143] op_sel_hi:[1,0]
	v_pk_mul_f32 v[14:15], v[14:15], v[142:143] op_sel_hi:[1,0]
	v_pk_mul_f32 v[12:13], v[12:13], v[160:161]
	v_pk_mul_f32 v[14:15], v[14:15], v[162:163]
	global_store_dwordx4 v176, v[12:15], s[52:53]
	v_pk_mul_f32 v[8:9], v[8:9], v[142:143] op_sel_hi:[1,0]
	v_pk_mul_f32 v[10:11], v[10:11], v[142:143] op_sel_hi:[1,0]
	v_pk_mul_f32 v[8:9], v[8:9], v[164:165]
	v_pk_mul_f32 v[10:11], v[10:11], v[166:167]
	global_store_dwordx4 v176, v[8:11], s[52:53] offset:16
	v_pk_mul_f32 v[4:5], v[4:5], v[142:143] op_sel_hi:[1,0]
	v_pk_mul_f32 v[6:7], v[6:7], v[142:143] op_sel_hi:[1,0]
	v_pk_mul_f32 v[4:5], v[4:5], v[168:169]
	v_pk_mul_f32 v[6:7], v[6:7], v[170:171]
	global_store_dwordx4 v176, v[4:7], s[52:53] offset:512
	v_pk_mul_f32 v[0:1], v[0:1], v[142:143] op_sel_hi:[1,0]
	v_pk_mul_f32 v[2:3], v[2:3], v[142:143] op_sel_hi:[1,0]
	v_pk_mul_f32 v[0:1], v[0:1], v[172:173]
	v_pk_mul_f32 v[2:3], v[2:3], v[174:175]
	global_store_dwordx4 v176, v[0:3], s[52:53] offset:528
	s_barrier
